# tail-convert slot boundaries moved down: B1 16896->13824, B3 28928->26112, B4 40192->36352 (rebalance weight conversion across GEMM tails)
# speedup vs baseline: 1.0106x; 1.0106x over previous
; #define LAS __attribute__((address_space(3)))
; __device__ __forceinline__ TrItem p0_item_of(const Params& p, int it, int lane) {
;     const float* W; bf16* WT; int K, N, map, r = it, f8 = 0;
;     ...
;     if (r < TR_FI) TR_FFN_IN(0)
;     else if ((r -= TR_FI) < TR_FO) TR_FFN_OUT(0)
;     else if ((r -= TR_FO) < TR_IN) { W = p.in[IN_EWI]; WT = (bf16*)(p.ws + WS_WEI); K = D; N = D_EIN; map = 2; }
;     else if ((r -= TR_IN) < TR_OUT) { W = p.in[IN_EWO]; WT = (bf16*)(p.ws + WS_WEO); K = D; N = D; map = 0; }
;     else if ((r -= TR_OUT) < TR_FI) TR_FFN_IN(1)
;     else if ((r -= TR_FI) < TR_FO) TR_FFN_OUT(1)
;     else if ((r -= TR_FO) < TR_FI) TR_FFN_IN(2)
;     else if ((r -= TR_FI) < TR_FO) TR_FFN_OUT(2)
;     else if ((r -= TR_FO) < TR_IN) { W = p.in[IN_OWI]; WT = (bf16*)(p.ws + WS_WOI); K = D; N = D_OIN; map = 3; }
;     else if ((r -= TR_IN) < TR_OUT) { W = p.in[IN_OWO]; WT = (bf16*)(p.ws + WS_WOO); K = D; N = D; map = 0; }
;     else if ((r -= TR_OUT) < TR_FI) TR_FFN_IN(3)
;     else { r -= TR_FI; TR_FFN_OUT(3) }
;     ...
;     const int nblk = N / 64, kb = r / nblk, nb = r % nblk, k0 = 64 * kb, n0 = 64 * nb;
; __device__ __forceinline__ void tail_convert(const Params& p, LAS unsigned char* lds, int slot, int units, int lane, int wave) {
;     const int G = gridDim.x, c = blockIdx.x, rem = units % G;
;     if (rem != 0 && c < rem) return;
;     const int nw = rem ? G - rem : G, j = rem ? c - rem : c;
;     tr_range(p, lds, TR_SLOT[slot] + j * 8 + wave, nw * 8, TR_SLOT[slot + 1], lane, wave);
.LBB0_226:
	s_abs_i32 s0, s97
	v_cvt_f32_u32_e32 v2, s0
	s_sub_i32 s1, 0, s0
	v_rcp_iflag_f32_e32 v2, v2
	s_nop 0
	v_mul_f32_e32 v2, 0x4f7ffffe, v2
	v_cvt_u32_f32_e32 v2, v2
	s_nop 0
	v_readfirstlane_b32 s2, v2
	s_mul_i32 s1, s1, s2
	s_mul_hi_u32 s1, s2, s1
	s_add_i32 s2, s2, s1
	s_mul_hi_u32 s1, s2, 0xc60
	s_mul_i32 s1, s1, s0
	s_sub_i32 s1, 0xc60, s1
	s_sub_i32 s2, s1, s0
	s_cmp_ge_u32 s1, s0
	s_cselect_b32 s1, s2, s1
	s_sub_i32 s2, s1, s0
	s_cmp_ge_u32 s1, s0
	s_cselect_b32 s12, s2, s1
	s_cmp_lg_u32 s12, 0
	s_cselect_b64 s[0:1], -1, 0
	s_cmp_lt_i32 s86, s12
	s_cselect_b64 s[2:3], -1, 0
	s_and_b64 s[0:1], s[0:1], s[2:3]
	s_and_b64 vcc, exec, s[0:1]
	s_cbranch_vccnz .LBB0_300
	s_sub_i32 s0, s86, s12
	s_lshl_b32 s13, s0, 3
	v_readlane_b32 s0, v253, 31
	s_add_i32 s13, s13, s0
	s_add_i32 s18, s13, 0x1600
	s_cmpk_gt_i32 s18, 0x35ff
	s_cbranch_scc1 .LBB0_300
	s_mov_b32 s1, 1
	s_cmp_gt_u32 s13, 0x7fffe9ff
	s_mov_b32 s21, 0
	s_cbranch_scc1 .LBB0_233
	s_cmpk_lt_u32 s18, 0x2100
	s_cbranch_scc1 .LBB0_234
	s_cmpk_gt_u32 s18, 0x2aff
	s_cbranch_scc0 .LBB0_235
	s_cmpk_gt_u32 s18, 0x2eff
	s_cbranch_scc0 .LBB0_236
	v_readlane_b32 s36, v253, 10
	v_readlane_b32 s48, v253, 22
	v_readlane_b32 s49, v253, 23
	v_readlane_b32 s50, v253, 24
	v_readlane_b32 s51, v253, 25
	s_mov_b64 s[28:29], s[48:49]
	s_add_i32 s14, s13, 0xffffe700
	s_mov_b64 s[30:31], s[50:51]
	s_add_u32 s2, s30, 0x5800000
	v_readlane_b32 s37, v253, 11
	v_readlane_b32 s38, v253, 12
	v_readlane_b32 s39, v253, 13
	v_readlane_b32 s40, v253, 14
	v_readlane_b32 s41, v253, 15
	v_readlane_b32 s42, v253, 16
	v_readlane_b32 s43, v253, 17
	v_readlane_b32 s44, v253, 18
	v_readlane_b32 s45, v253, 19
	v_readlane_b32 s46, v253, 20
	v_readlane_b32 s47, v253, 21
	s_addc_u32 s3, s31, 0
	s_mov_b64 s[0:1], 0
	s_branch .LBB0_237

; #define LDS_WAIT() asm volatile("s_waitcnt lgkmcnt(0)" ::: "memory")
; __device__ __forceinline__ TrItem p0_item_of(const Params& p, int it, int lane) {
;     ...
;     if (r < TR_FI) TR_FFN_IN(0)
;     else if ((r -= TR_FI) < TR_FO) TR_FFN_OUT(0)
;     else if ((r -= TR_FO) < TR_IN) { W = p.in[IN_EWI]; WT = (bf16*)(p.ws + WS_WEI); K = D; N = D_EIN; map = 2; }
;     else if ((r -= TR_IN) < TR_OUT) { W = p.in[IN_EWO]; WT = (bf16*)(p.ws + WS_WEO); K = D; N = D; map = 0; }
;     else if ((r -= TR_OUT) < TR_FI) TR_FFN_IN(1)
;     else if ((r -= TR_FI) < TR_FO) TR_FFN_OUT(1)
;     else if ((r -= TR_FO) < TR_FI) TR_FFN_IN(2)
;     else if ((r -= TR_FI) < TR_FO) TR_FFN_OUT(2)
;     else if ((r -= TR_FO) < TR_IN) { W = p.in[IN_OWI]; WT = (bf16*)(p.ws + WS_WOI); K = D; N = D_OIN; map = 3; }
;     else if ((r -= TR_IN) < TR_OUT) { W = p.in[IN_OWO]; WT = (bf16*)(p.ws + WS_WOO); K = D; N = D; map = 0; }
;     else if ((r -= TR_OUT) < TR_FI) TR_FFN_IN(3)
;     else { r -= TR_FI; TR_FFN_OUT(3) }
; __device__ __forceinline__ void tr_range(const Params& p, LAS unsigned char* lds, int first, int stride, int end, int lane, int wave) {
;     ...
;     for (int it = first; it < end; it += stride) {
; #pragma unroll
;         for (int i = 0; i < 64; ++i) scr[i * 65 + lane] = ra[i];
;         const bool more = it + stride < end;
;         TrItem nxt = cur;
;         if (more) { nxt = p0_item_of(p, it + stride, lane);
; #pragma unroll
;             for (int i = 0; i < 64; ++i) ra[i] = nxt.src[(size_t)i * nxt.N]; }
;         LDS_WAIT(); asm volatile("" ::: "memory");
.LBB0_265:
	s_waitcnt lgkmcnt(0)
	s_add_i32 s23, s23, s20
	s_add_i32 s0, s24, s23
	s_cmpk_lt_i32 s0, 0x3600
	s_mov_b32 s21, s16
	s_mov_b32 s19, s17
	s_mov_b64 s[2:3], s[8:9]
	s_cbranch_scc0 .LBB0_300
.LBB0_266:
	v_add_u32_e32 v85, 0x400, v3
	s_waitcnt vmcnt(0)
	ds_write2_b32 v3, v15, v31 offset1:65
	ds_write2_b32 v3, v30, v27 offset0:130 offset1:195
	ds_write2_b32 v85, v25, v23 offset0:4 offset1:69
	ds_write2_b32 v85, v21, v19 offset0:134 offset1:199
	v_add_u32_e32 v85, 0x800, v3
	ds_write2_b32 v85, v74, v73 offset0:8 offset1:73
	ds_write2_b32 v85, v72, v71 offset0:138 offset1:203
	v_add_u32_e32 v85, 0xc00, v3
	ds_write2_b32 v85, v70, v69 offset0:12 offset1:77
	ds_write2_b32 v85, v68, v67 offset0:142 offset1:207
	v_add_u32_e32 v85, 0x1000, v3
	ds_write2_b32 v85, v79, v66 offset0:16 offset1:81
	ds_write2_b32 v85, v65, v64 offset0:146 offset1:211
	v_add_u32_e32 v85, 0x1400, v3
	ds_write2_b32 v85, v63, v62 offset0:20 offset1:85
	ds_write2_b32 v85, v61, v60 offset0:150 offset1:215
	v_add_u32_e32 v85, 0x1800, v3
	ds_write2_b32 v85, v78, v59 offset0:24 offset1:89
	ds_write2_b32 v85, v58, v57 offset0:154 offset1:219
	v_add_u32_e32 v85, 0x1c00, v3
	ds_write2_b32 v85, v56, v55 offset0:28 offset1:93
	ds_write2_b32 v85, v54, v53 offset0:158 offset1:223
	v_add_u32_e32 v85, 0x2000, v3
	ds_write2_b32 v85, v77, v52 offset0:32 offset1:97
	ds_write2_b32 v85, v51, v50 offset0:162 offset1:227
	v_add_u32_e32 v85, 0x2400, v3
	ds_write2_b32 v85, v49, v48 offset0:36 offset1:101
	ds_write2_b32 v85, v47, v46 offset0:166 offset1:231
	v_add_u32_e32 v85, 0x2800, v3
	ds_write2_b32 v85, v76, v45 offset0:40 offset1:105
	ds_write2_b32 v85, v44, v43 offset0:170 offset1:235
	v_add_u32_e32 v85, 0x2c00, v3
	ds_write2_b32 v85, v42, v41 offset0:44 offset1:109
	ds_write2_b32 v85, v40, v39 offset0:174 offset1:239
	v_add_u32_e32 v85, 0x3000, v3
	ds_write2_b32 v85, v75, v38 offset0:48 offset1:113
	ds_write2_b32 v85, v37, v36 offset0:178 offset1:243
	v_add_u32_e32 v85, 0x3400, v3
	s_add_i32 s0, s22, s23
	ds_write2_b32 v85, v35, v34 offset0:52 offset1:117
	ds_write2_b32 v85, v33, v32 offset0:182 offset1:247
	v_add_u32_e32 v85, 0x3800, v3
	s_add_i32 s18, s18, s20
	s_add_i32 s28, s0, 0x1600
	ds_write2_b32 v85, v28, v17 offset0:56 offset1:121
	ds_write2_b32 v85, v84, v83 offset0:186 offset1:251
	v_add_u32_e32 v85, 0x3c00, v3
	s_cmpk_gt_i32 s28, 0x35ff
	ds_write2_b32 v85, v82, v81 offset0:60 offset1:125
	ds_write2_b32 v85, v80, v29 offset0:190 offset1:255
	s_cbranch_scc1 .LBB0_295
	s_cmpk_lt_i32 s28, 0x1600
	s_cbranch_scc1 .LBB0_273
	v_readlane_b32 s36, v253, 32
	v_readlane_b32 s37, v253, 33
	s_cmpk_gt_u32 s28, 0x20ff
	s_mov_b64 s[8:9], -1
	s_mov_b64 s[12:13], s[36:37]
	s_mov_b64 s[16:17], -1
	v_readlane_b32 s38, v253, 34
	v_readlane_b32 s39, v253, 35
	v_readlane_b32 s40, v253, 36
	v_readlane_b32 s41, v253, 37
	v_readlane_b32 s42, v253, 38
	v_readlane_b32 s43, v253, 39
	v_readlane_b32 s44, v253, 40
	v_readlane_b32 s45, v253, 41
	v_readlane_b32 s46, v253, 42
	v_readlane_b32 s47, v253, 43
	v_readlane_b32 s48, v253, 44
	v_readlane_b32 s49, v253, 45
	v_readlane_b32 s50, v253, 46
	v_readlane_b32 s51, v253, 47
	s_cbranch_scc0 .LBB0_277
	s_cmpk_gt_u32 s28, 0x2aff
	s_cbranch_scc0 .LBB0_274
	s_cmpk_gt_u32 s28, 0x2eff
	s_cbranch_scc0 .LBB0_298
	s_add_i32 s27, s0, 0xffffe700
	s_mov_b64 s[12:13], s[6:7]
	s_mov_b64 s[16:17], 0
	s_mov_b32 s26, 1
	s_cbranch_execz .LBB0_299
	s_mov_b64 s[10:11], 0x3000000
	s_movk_i32 s0, 0x2c00
	s_mov_b64 s[14:15], 0
	s_andn2_b64 vcc, exec, s[16:17]
	s_cbranch_vccz .LBB0_275
	s_branch .LBB0_276

; #define LAS __attribute__((address_space(3)))
; __device__ __forceinline__ TrItem p0_item_of(const Params& p, int it, int lane) {
;     const float* W; bf16* WT; int K, N, map, r = it, f8 = 0;
;     ...
;     if (r < TR_FI) TR_FFN_IN(0)
;     else if ((r -= TR_FI) < TR_FO) TR_FFN_OUT(0)
;     else if ((r -= TR_FO) < TR_IN) { W = p.in[IN_EWI]; WT = (bf16*)(p.ws + WS_WEI); K = D; N = D_EIN; map = 2; }
;     else if ((r -= TR_IN) < TR_OUT) { W = p.in[IN_EWO]; WT = (bf16*)(p.ws + WS_WEO); K = D; N = D; map = 0; }
;     else if ((r -= TR_OUT) < TR_FI) TR_FFN_IN(1)
;     else if ((r -= TR_FI) < TR_FO) TR_FFN_OUT(1)
;     else if ((r -= TR_FO) < TR_FI) TR_FFN_IN(2)
;     else if ((r -= TR_FI) < TR_FO) TR_FFN_OUT(2)
;     else if ((r -= TR_FO) < TR_IN) { W = p.in[IN_OWI]; WT = (bf16*)(p.ws + WS_WOI); K = D; N = D_OIN; map = 3; }
;     else if ((r -= TR_IN) < TR_OUT) { W = p.in[IN_OWO]; WT = (bf16*)(p.ws + WS_WOO); K = D; N = D; map = 0; }
;     else if ((r -= TR_OUT) < TR_FI) TR_FFN_IN(3)
;     else { r -= TR_FI; TR_FFN_OUT(3) }
;     ...
;     const int nblk = N / 64, kb = r / nblk, nb = r % nblk, k0 = 64 * kb, n0 = 64 * nb;
; __device__ __forceinline__ void tail_convert(const Params& p, LAS unsigned char* lds, int slot, int units, int lane, int wave) {
;     const int G = gridDim.x, c = blockIdx.x, rem = units % G;
;     if (rem != 0 && c < rem) return;
;     const int nw = rem ? G - rem : G, j = rem ? c - rem : c;
;     tr_range(p, lds, TR_SLOT[slot] + j * 8 + wave, nw * 8, TR_SLOT[slot + 1], lane, wave);
.LBB0_548:
	s_abs_i32 s0, s97
	v_cvt_f32_u32_e32 v2, s0
	s_sub_i32 s1, 0, s0
	v_rcp_iflag_f32_e32 v2, v2
	s_nop 0
	v_mul_f32_e32 v2, 0x4f7ffffe, v2
	v_cvt_u32_f32_e32 v2, v2
	s_nop 0
	v_readfirstlane_b32 s2, v2
	s_mul_i32 s1, s1, s2
	s_mul_hi_u32 s1, s2, s1
	s_add_i32 s2, s2, s1
	s_mul_hi_u32 s1, s2, 0x5a0
	s_mul_i32 s1, s1, s0
	s_sub_i32 s1, 0x5a0, s1
	s_sub_i32 s2, s1, s0
	s_cmp_ge_u32 s1, s0
	s_cselect_b32 s1, s2, s1
	s_sub_i32 s2, s1, s0
	s_cmp_ge_u32 s1, s0
	s_cselect_b32 s14, s2, s1
	s_cmp_lg_u32 s14, 0
	s_cselect_b64 s[0:1], -1, 0
	s_cmp_lt_i32 s86, s14
	s_cselect_b64 s[2:3], -1, 0
	s_and_b64 s[0:1], s[0:1], s[2:3]
	s_and_b64 vcc, exec, s[0:1]
	s_cbranch_vccnz .LBB0_624
	s_sub_i32 s0, s86, s14
	s_addk_i32 s0, 0xfe80
	s_lshl_b32 s16, s0, 3
	v_readlane_b32 s0, v253, 31
	s_add_i32 s16, s16, s0
	s_add_i32 s18, s16, 0x4200
	s_cmpk_gt_i32 s18, 0x44ff
	s_cbranch_scc1 .LBB0_624
	s_mov_b32 s1, 1
	s_cmpk_lt_i32 s18, 0x1600
	s_mov_b32 s21, 0
	s_cbranch_scc1 .LBB0_555
	s_cmpk_gt_u32 s18, 0x20ff
	s_mov_b64 s[2:3], -1
	s_cbranch_scc0 .LBB0_556
	s_cmpk_gt_u32 s18, 0x2aff
	s_cbranch_scc0 .LBB0_558
	s_cmpk_gt_u32 s18, 0x2eff
	s_cbranch_scc0 .LBB0_559
	v_readlane_b32 s36, v253, 10
	v_readlane_b32 s48, v253, 22
	v_readlane_b32 s49, v253, 23
	v_readlane_b32 s50, v253, 24
	v_readlane_b32 s51, v253, 25
	s_mov_b64 s[20:21], s[48:49]
	s_add_i32 s15, s16, 0x1300
	s_mov_b64 s[22:23], s[50:51]
	s_add_u32 s6, s22, 0x5800000
	v_readlane_b32 s37, v253, 11
	v_readlane_b32 s38, v253, 12
	v_readlane_b32 s39, v253, 13
	v_readlane_b32 s40, v253, 14
	v_readlane_b32 s41, v253, 15
	v_readlane_b32 s42, v253, 16
	v_readlane_b32 s43, v253, 17
	v_readlane_b32 s44, v253, 18
	v_readlane_b32 s45, v253, 19
	v_readlane_b32 s46, v253, 20
	v_readlane_b32 s47, v253, 21
	s_addc_u32 s7, s23, 0
	s_mov_b64 s[0:1], 0
	s_branch .LBB0_560

; #define LAS __attribute__((address_space(3)))
; __device__ __forceinline__ TrItem p0_item_of(const Params& p, int it, int lane) {
;     ...
;     const int nblk = N / 64, kb = r / nblk, nb = r % nblk, k0 = 64 * kb, n0 = 64 * nb;
;     TrItem t; t.src = W + (size_t)k0 * N + srccol(map, n0 + lane); t.N = N; t.K = K; t.fp8 = f8;
;     t.dst = f8 ? (bf16*)((unsigned char*)WT + (size_t)n0 * K + k0) : WT + (size_t)n0 * K + k0; return t;
; }
; __device__ __forceinline__ void tr_range(const Params& p, LAS unsigned char* lds, int first, int stride, int end, int lane, int wave) {
;     LAS float* scr = (LAS float*)(lds + wave * (64 * 65 * 4));
;     if (first >= end) return;
;     float ra[64];
;     TrItem cur = p0_item_of(p, first, lane);
; #pragma unroll
;     for (int i = 0; i < 64; ++i) ra[i] = cur.src[(size_t)i * cur.N];
.LBB0_587:
	s_add_u32 s15, s88, s8
	s_addc_u32 s9, s89, s9
	s_lshl_b32 s10, s13, 6
	s_ashr_i32 s11, s10, 31
	v_readlane_b32 s23, v253, 31
	s_mul_i32 s13, s11, s0
	s_mul_hi_u32 s16, s10, s0
	s_sub_i32 s1, s97, s14
	s_mul_i32 s8, s23, 0x4100
	s_add_i32 s17, s16, s13
	s_mul_i32 s16, s10, s0
	s_lshl_b32 s20, s1, 3
	s_add_i32 s8, s8, 0
	s_lshl_b64 s[16:17], s[16:17], 2
	s_add_u32 s6, s6, s16
	s_addc_u32 s7, s7, s17
	v_ashrrev_i32_e32 v3, 31, v2
	v_lshl_add_u64 v[2:3], v[2:3], 2, s[6:7]
	s_mul_hi_i32 s7, s12, s19
	s_mul_i32 s6, s12, s19
	s_lshl_b64 s[12:13], s[6:7], 1
	s_add_u32 s16, s15, s12
	s_addc_u32 s17, s9, s13
	s_lshl_b64 s[12:13], s[10:11], 1
	s_add_u32 s12, s16, s12
	s_addc_u32 s13, s17, s13
	s_add_u32 s6, s15, s6
	s_addc_u32 s7, s9, s7
	s_add_u32 s6, s6, s10
	s_addc_u32 s7, s7, s11
	s_mov_b32 s1, 0
	s_and_b64 s[2:3], s[2:3], exec
	s_cselect_b32 s3, s13, s7
	s_cselect_b32 s2, s12, s6
	s_mul_i32 s6, s0, 63
	s_mov_b32 s7, s1
	v_lshl_add_u64 v[4:5], s[6:7], 2, v[2:3]
	s_mul_i32 s6, s0, 62
	v_lshl_add_u64 v[6:7], s[6:7], 2, v[2:3]
	s_mul_i32 s6, s0, 61
	v_lshl_add_u64 v[8:9], s[6:7], 2, v[2:3]
	s_mul_i32 s6, s0, 60
	v_lshl_add_u64 v[10:11], s[6:7], 2, v[2:3]
	s_mul_i32 s6, s0, 59
	v_lshl_add_u64 v[12:13], s[6:7], 2, v[2:3]
	s_mul_i32 s6, s0, 58
	v_lshl_add_u64 v[14:15], s[6:7], 2, v[2:3]
	s_mul_i32 s6, s0, 57
	v_lshl_add_u64 v[16:17], s[6:7], 2, v[2:3]
	s_mul_i32 s6, s0, 56
	v_lshl_add_u64 v[18:19], s[6:7], 2, v[2:3]
	s_mul_i32 s6, s0, 55
	v_lshl_add_u64 v[20:21], s[6:7], 2, v[2:3]
	s_mul_i32 s6, s0, 54
	v_lshl_add_u64 v[22:23], s[6:7], 2, v[2:3]
	s_mul_i32 s6, s0, 53
	v_lshl_add_u64 v[24:25], s[6:7], 2, v[2:3]
	s_mul_i32 s6, s0, 52
	v_lshl_add_u64 v[26:27], s[6:7], 2, v[2:3]
	s_mul_i32 s6, s0, 51
	v_lshl_add_u64 v[30:31], s[6:7], 2, v[2:3]
	s_mul_i32 s6, s0, 50
	v_lshl_add_u64 v[38:39], s[6:7], 2, v[2:3]
	s_mul_i32 s6, s0, 49
	v_lshl_add_u64 v[40:41], s[6:7], 2, v[2:3]
	s_mul_i32 s6, s0, 48
	global_load_dword v28, v[18:19], off
	global_load_dword v32, v[20:21], off
	global_load_dword v33, v[22:23], off
	global_load_dword v34, v[24:25], off
	global_load_dword v35, v[26:27], off
	global_load_dword v36, v[30:31], off
	global_load_dword v37, v[38:39], off
	s_nop 0
	global_load_dword v38, v[40:41], off
	v_lshl_add_u64 v[18:19], s[6:7], 2, v[2:3]
	s_mul_i32 s6, s0, 47
	v_lshl_add_u64 v[20:21], s[6:7], 2, v[2:3]
	s_mul_i32 s6, s0, 46
	v_lshl_add_u64 v[22:23], s[6:7], 2, v[2:3]
	s_mul_i32 s6, s0, 45
	v_lshl_add_u64 v[24:25], s[6:7], 2, v[2:3]
	s_mul_i32 s6, s0, 44
	v_lshl_add_u64 v[26:27], s[6:7], 2, v[2:3]
	s_mul_i32 s6, s0, 43
	v_lshl_add_u64 v[30:31], s[6:7], 2, v[2:3]
	s_mul_i32 s6, s0, 42
	v_lshl_add_u64 v[44:45], s[6:7], 2, v[2:3]
	s_mul_i32 s6, s0, 41
	v_lshl_add_u64 v[46:47], s[6:7], 2, v[2:3]
	s_mul_i32 s6, s0, 40
	global_load_dword v75, v[18:19], off
	global_load_dword v39, v[20:21], off
	global_load_dword v40, v[22:23], off
	global_load_dword v41, v[24:25], off
	global_load_dword v42, v[26:27], off
	global_load_dword v43, v[30:31], off
	s_nop 0
	global_load_dword v44, v[44:45], off
	s_nop 0
	global_load_dword v45, v[46:47], off
	v_lshl_add_u64 v[18:19], s[6:7], 2, v[2:3]
	s_mul_i32 s6, s0, 39
	v_lshl_add_u64 v[20:21], s[6:7], 2, v[2:3]
	s_mul_i32 s6, s0, 38
	v_lshl_add_u64 v[22:23], s[6:7], 2, v[2:3]
	s_mul_i32 s6, s0, 37
	v_lshl_add_u64 v[24:25], s[6:7], 2, v[2:3]
	s_mul_i32 s6, s0, 36
	v_lshl_add_u64 v[26:27], s[6:7], 2, v[2:3]
	s_mul_i32 s6, s0, 35
	v_lshl_add_u64 v[30:31], s[6:7], 2, v[2:3]
	s_mul_i32 s6, s0, 34
	v_lshl_add_u64 v[52:53], s[6:7], 2, v[2:3]
	s_mul_i32 s6, s0, 33
	v_lshl_add_u64 v[54:55], s[6:7], 2, v[2:3]
	s_lshl_b32 s6, s0, 5
	global_load_dword v76, v[18:19], off
	global_load_dword v46, v[20:21], off
	global_load_dword v47, v[22:23], off
	global_load_dword v48, v[24:25], off
	global_load_dword v49, v[26:27], off
	global_load_dword v50, v[30:31], off
	global_load_dword v51, v[52:53], off
	s_nop 0
	global_load_dword v52, v[54:55], off
	v_lshl_add_u64 v[18:19], s[6:7], 2, v[2:3]
	s_mul_i32 s6, s0, 31
	v_lshl_add_u64 v[20:21], s[6:7], 2, v[2:3]
	s_mul_i32 s6, s0, 30
	v_lshl_add_u64 v[22:23], s[6:7], 2, v[2:3]
	s_mul_i32 s6, s0, 29
	v_lshl_add_u64 v[24:25], s[6:7], 2, v[2:3]
	s_mul_i32 s6, s0, 28
	v_lshl_add_u64 v[26:27], s[6:7], 2, v[2:3]
	s_mul_i32 s6, s0, 27
	v_lshl_add_u64 v[30:31], s[6:7], 2, v[2:3]
	s_mul_i32 s6, s0, 26
	v_lshl_add_u64 v[58:59], s[6:7], 2, v[2:3]
	s_mul_i32 s6, s0, 25
	v_lshl_add_u64 v[60:61], s[6:7], 2, v[2:3]
	s_mul_i32 s6, s0, 24
	global_load_dword v77, v[18:19], off
	global_load_dword v53, v[20:21], off
	global_load_dword v54, v[22:23], off
	global_load_dword v55, v[24:25], off
; __device__ __forceinline__ unsigned cvt_pk_bf16(float lo, float hi) { unsigned r; asm volatile("v_cvt_pk_bf16_f32 %0, %1, %2" : "=v"(r) : "v"(lo), "v"(hi)); return r; }
; #define LAS __attribute__((address_space(3)))
; #define LDS_WAIT() asm volatile("s_waitcnt lgkmcnt(0)" ::: "memory")
; __device__ __forceinline__ void tr_range(const Params& p, LAS unsigned char* lds, int first, int stride, int end, int lane, int wave) {
;     LAS float* scr = (LAS float*)(lds + wave * (64 * 65 * 4));
;     if (first >= end) return;
;     float ra[64];
;     TrItem cur = p0_item_of(p, first, lane);
; #pragma unroll
;     for (int i = 0; i < 64; ++i) ra[i] = cur.src[(size_t)i * cur.N];
; #pragma unroll 1
;     for (int it = first; it < end; it += stride) {
; #pragma unroll
;         for (int i = 0; i < 64; ++i) scr[i * 65 + lane] = ra[i];
;         const bool more = it + stride < end;
;         TrItem nxt = cur;
;         if (more) { nxt = p0_item_of(p, it + stride, lane);
; #pragma unroll
;             for (int i = 0; i < 64; ++i) ra[i] = nxt.src[(size_t)i * nxt.N]; }
;         LDS_WAIT(); asm volatile("" ::: "memory");
;         if (cur.fp8) {
;             const int c = lane & 3;
; #pragma unroll
;             for (int j = 0; j < 4; ++j) { const int n = (lane >> 2) + 16 * j; const LAS float* s = scr + (16 * c) * 65 + n;
;                 u32x4 o;
;                 o.x = pk4_fp8(s[0 * 65] * W8_SCALE, s[1 * 65] * W8_SCALE, s[2 * 65] * W8_SCALE, s[3 * 65] * W8_SCALE);
;                 o.y = pk4_fp8(s[4 * 65] * W8_SCALE, s[5 * 65] * W8_SCALE, s[6 * 65] * W8_SCALE, s[7 * 65] * W8_SCALE);
;                 o.z = pk4_fp8(s[8 * 65] * W8_SCALE, s[9 * 65] * W8_SCALE, s[10 * 65] * W8_SCALE, s[11 * 65] * W8_SCALE);
;                 o.w = pk4_fp8(s[12 * 65] * W8_SCALE, s[13 * 65] * W8_SCALE, s[14 * 65] * W8_SCALE, s[15 * 65] * W8_SCALE);
;                 *(u32x4*)((unsigned char*)cur.dst + (size_t)n * cur.K + 16 * c) = o; }
;         } else {
;         const int c = lane & 7;
; #pragma unroll
;         for (int j = 0; j < 8; ++j) { const int n = (lane >> 3) + 8 * j; const LAS float* s = scr + (8 * c) * 65 + n;
;             u32x4 o; o.x = pg8::cvt_pk_bf16(s[0 * 65], s[1 * 65]); o.y = pg8::cvt_pk_bf16(s[2 * 65], s[3 * 65]); o.z = pg8::cvt_pk_bf16(s[4 * 65], s[5 * 65]); o.w = pg8::cvt_pk_bf16(s[6 * 65], s[7 * 65]);
	global_load_dword v56, v[26:27], off
	global_load_dword v57, v[30:31], off
	s_nop 0
	global_load_dword v58, v[58:59], off
	s_nop 0
	global_load_dword v59, v[60:61], off
	v_lshl_add_u64 v[18:19], s[6:7], 2, v[2:3]
	s_mul_i32 s6, s0, 23
	v_lshl_add_u64 v[20:21], s[6:7], 2, v[2:3]
	s_mul_i32 s6, s0, 22
	v_lshl_add_u64 v[22:23], s[6:7], 2, v[2:3]
	s_mul_i32 s6, s0, 21
	v_lshl_add_u64 v[24:25], s[6:7], 2, v[2:3]
	s_mul_i32 s6, s0, 20
	v_lshl_add_u64 v[26:27], s[6:7], 2, v[2:3]
	s_mul_i32 s6, s0, 19
	v_lshl_add_u64 v[30:31], s[6:7], 2, v[2:3]
	s_mul_i32 s6, s0, 18
	v_lshl_add_u64 v[66:67], s[6:7], 2, v[2:3]
	s_mul_i32 s6, s0, 17
	v_lshl_add_u64 v[68:69], s[6:7], 2, v[2:3]
	s_lshl_b32 s6, s0, 4
	global_load_dword v78, v[18:19], off
	global_load_dword v60, v[20:21], off
	global_load_dword v61, v[22:23], off
	global_load_dword v62, v[24:25], off
	global_load_dword v63, v[26:27], off
	global_load_dword v64, v[30:31], off
	global_load_dword v65, v[66:67], off
	s_nop 0
	global_load_dword v66, v[68:69], off
	v_lshl_add_u64 v[18:19], s[6:7], 2, v[2:3]
	s_mul_i32 s6, s0, 15
	v_lshl_add_u64 v[20:21], s[6:7], 2, v[2:3]
	s_mul_i32 s6, s0, 14
	v_lshl_add_u64 v[22:23], s[6:7], 2, v[2:3]
	s_mul_i32 s6, s0, 13
	v_lshl_add_u64 v[24:25], s[6:7], 2, v[2:3]
	s_mul_i32 s6, s0, 12
	v_lshl_add_u64 v[26:27], s[6:7], 2, v[2:3]
	s_mul_i32 s6, s0, 11
	v_lshl_add_u64 v[30:31], s[6:7], 2, v[2:3]
	s_mul_i32 s6, s0, 10
	v_lshl_add_u64 v[72:73], s[6:7], 2, v[2:3]
	s_mul_i32 s6, s0, 9
	v_lshl_add_u64 v[80:81], s[6:7], 2, v[2:3]
	s_lshl_b32 s6, s0, 3
	global_load_dword v79, v[18:19], off
	global_load_dword v67, v[20:21], off
	global_load_dword v68, v[22:23], off
	global_load_dword v69, v[24:25], off
	global_load_dword v70, v[26:27], off
	global_load_dword v71, v[30:31], off
	s_nop 0
	global_load_dword v72, v[72:73], off
	s_nop 0
	global_load_dword v73, v[80:81], off
	v_lshl_add_u64 v[18:19], s[6:7], 2, v[2:3]
	s_mul_i32 s6, s0, 7
	v_lshl_add_u64 v[20:21], s[6:7], 2, v[2:3]
	s_mul_i32 s6, s0, 6
	v_lshl_add_u64 v[22:23], s[6:7], 2, v[2:3]
	s_mul_i32 s6, s0, 5
	v_lshl_add_u64 v[24:25], s[6:7], 2, v[2:3]
	s_lshl_b32 s6, s0, 2
	v_lshl_add_u64 v[26:27], s[6:7], 2, v[2:3]
	s_mul_i32 s6, s0, 3
	v_lshl_add_u64 v[30:31], s[6:7], 2, v[2:3]
	s_lshl_b32 s6, s0, 1
	v_lshl_add_u64 v[80:81], s[6:7], 2, v[2:3]
	v_lshl_add_u64 v[82:83], s[0:1], 2, v[2:3]
	global_load_dword v74, v[18:19], off
	s_nop 0
	global_load_dword v19, v[20:21], off
	s_nop 0
	global_load_dword v21, v[22:23], off
	s_nop 0
	global_load_dword v23, v[24:25], off
	s_nop 0
	global_load_dword v25, v[26:27], off
	s_nop 0
	global_load_dword v27, v[30:31], off
	s_nop 0
	global_load_dword v30, v[80:81], off
	global_load_dword v31, v[82:83], off
	global_load_dword v29, v[4:5], off
	s_nop 0
	global_load_dword v80, v[6:7], off
	global_load_dword v81, v[8:9], off
	global_load_dword v82, v[10:11], off
	global_load_dword v83, v[12:13], off
	global_load_dword v84, v[14:15], off
	s_nop 0
	global_load_dword v17, v[16:17], off
	s_nop 0
	global_load_dword v15, v[2:3], off
	v_readlane_b32 s36, v253, 10
	v_readlane_b32 s48, v253, 22
	v_readlane_b32 s49, v253, 23
	v_lshlrev_b32_e32 v4, 3, v0
	v_readlane_b32 s50, v253, 24
	v_readlane_b32 s51, v253, 25
	s_mov_b64 s[24:25], s[48:49]
	v_lshrrev_b32_e32 v6, 3, v1
	v_and_b32_e32 v4, 56, v4
	s_mov_b64 s[26:27], s[50:51]
	v_mul_u32_u24_e32 v8, 0x104, v130
	v_mul_u32_u24_e32 v11, 0x104, v4
	v_and_b32_e32 v9, 60, v1
	v_lshlrev_b32_e32 v13, 2, v6
	s_add_u32 s6, s26, 0x5800000
	v_lshl_add_u32 v3, v1, 2, s8
	v_add3_u32 v9, s8, v8, v9
	v_add3_u32 v11, s8, v11, v13
	s_addc_u32 s7, s27, 0
	s_lshl_b32 s0, s97, 3
	s_lshl_b32 s8, s14, 4
	s_sub_i32 s22, s0, s8
	s_lshl_b32 s0, s86, 3
	s_addk_i32 s0, 0xf400
	v_lshrrev_b32_e32 v2, 2, v1
	v_mov_b32_e32 v5, 0
	s_add_i32 s23, s23, s0
	s_lshl_b32 s0, s14, 3
	v_and_b32_e32 v7, 31, v0
	v_mov_b32_e32 v131, v5
	v_or_b32_e32 v8, 16, v2
	v_or_b32_e32 v10, 32, v2
	v_or_b32_e32 v12, 48, v2
	v_or_b32_e32 v14, 8, v6
	v_or_b32_e32 v16, 16, v6
	v_or_b32_e32 v18, 24, v6
	v_or_b32_e32 v20, 32, v6
	v_or_b32_e32 v22, 40, v6
	v_or_b32_e32 v24, 48, v6
	v_or_b32_e32 v26, 56, v6
	s_sub_i32 s24, 0x4200, s0
	s_mov_b32 s25, 0xc3e00000
	v_lshlrev_b32_e32 v4, 1, v4
	v_mov_b32_e32 v13, 0x43e00000
	s_mov_b32 s16, s21
	s_mov_b64 s[8:9], s[2:3]
	s_mov_b32 s17, s19
	v_readlane_b32 s37, v253, 11
	v_readlane_b32 s38, v253, 12
	v_readlane_b32 s39, v253, 13
	v_readlane_b32 s40, v253, 14
	v_readlane_b32 s41, v253, 15
	v_readlane_b32 s42, v253, 16
	v_readlane_b32 s43, v253, 17
	v_readlane_b32 s44, v253, 18
	v_readlane_b32 s45, v253, 19
	v_readlane_b32 s46, v253, 20
	v_readlane_b32 s47, v253, 21
	s_branch .LBB0_590

; #define LAS __attribute__((address_space(3)))
; __device__ __forceinline__ TrItem p0_item_of(const Params& p, int it, int lane) {
;     const float* W; bf16* WT; int K, N, map, r = it, f8 = 0;
;     ...
;     if (r < TR_FI) TR_FFN_IN(0)
;     else if ((r -= TR_FI) < TR_FO) TR_FFN_OUT(0)
;     else if ((r -= TR_FO) < TR_IN) { W = p.in[IN_EWI]; WT = (bf16*)(p.ws + WS_WEI); K = D; N = D_EIN; map = 2; }
;     else if ((r -= TR_IN) < TR_OUT) { W = p.in[IN_EWO]; WT = (bf16*)(p.ws + WS_WEO); K = D; N = D; map = 0; }
;     else if ((r -= TR_OUT) < TR_FI) TR_FFN_IN(1)
;     else if ((r -= TR_FI) < TR_FO) TR_FFN_OUT(1)
;     else if ((r -= TR_FO) < TR_FI) TR_FFN_IN(2)
;     else if ((r -= TR_FI) < TR_FO) TR_FFN_OUT(2)
;     else if ((r -= TR_FO) < TR_IN) { W = p.in[IN_OWI]; WT = (bf16*)(p.ws + WS_WOI); K = D; N = D_OIN; map = 3; }
;     else if ((r -= TR_IN) < TR_OUT) { W = p.in[IN_OWO]; WT = (bf16*)(p.ws + WS_WOO); K = D; N = D; map = 0; }
;     else if ((r -= TR_OUT) < TR_FI) TR_FFN_IN(3)
;     else { r -= TR_FI; TR_FFN_OUT(3) }
;     ...
;     const int nblk = N / 64, kb = r / nblk, nb = r % nblk, k0 = 64 * kb, n0 = 64 * nb;
; __device__ __forceinline__ void tail_convert(const Params& p, LAS unsigned char* lds, int slot, int units, int lane, int wave) {
;     const int G = gridDim.x, c = blockIdx.x, rem = units % G;
;     if (rem != 0 && c < rem) return;
;     const int nw = rem ? G - rem : G, j = rem ? c - rem : c;
;     tr_range(p, lds, TR_SLOT[slot] + j * 8 + wave, nw * 8, TR_SLOT[slot + 1], lane, wave);
.LBB0_1106:
	s_abs_i32 s0, s97
	v_cvt_f32_u32_e32 v2, s0
	s_sub_i32 s1, 0, s0
	v_rcp_iflag_f32_e32 v2, v2
	s_nop 0
	v_mul_f32_e32 v2, 0x4f7ffffe, v2
	v_cvt_u32_f32_e32 v2, v2
	s_nop 0
	v_readfirstlane_b32 s2, v2
	s_mul_i32 s1, s1, s2
	s_mul_hi_u32 s1, s2, s1
	s_add_i32 s2, s2, s1
	s_mul_hi_u32 s1, s2, 0xc60
	s_mul_i32 s1, s1, s0
	s_sub_i32 s1, 0xc60, s1
	s_sub_i32 s2, s1, s0
	s_cmp_ge_u32 s1, s0
	s_cselect_b32 s1, s2, s1
	s_sub_i32 s2, s1, s0
	s_cmp_ge_u32 s1, s0
	s_cselect_b32 s30, s2, s1
	s_cmp_lg_u32 s30, 0
	s_cselect_b64 s[0:1], -1, 0
	s_cmp_lt_i32 s86, s30
	s_cselect_b64 s[2:3], -1, 0
	s_and_b64 s[0:1], s[0:1], s[2:3]
	s_and_b64 vcc, exec, s[0:1]
	s_cbranch_vccnz .LBB0_1211
	s_sub_i32 s0, s86, s30
	s_lshl_b32 s17, s0, 3
	v_readlane_b32 s0, v253, 31
	s_add_i32 s17, s17, s0
	s_add_i32 s33, s17, 0x4500
	s_cmpk_gt_i32 s33, 0x65ff
	s_cbranch_scc1 .LBB0_1211
	s_cmpk_gt_i32 s33, 0x15ff
	s_cbranch_scc0 .LBB0_1116
	s_cmpk_gt_u32 s33, 0x20ff
	s_cbranch_scc0 .LBB0_1117
	s_cmpk_gt_u32 s33, 0x2aff
	s_cbranch_scc0 .LBB0_1118
	s_cmpk_gt_u32 s33, 0x2eff
	s_cbranch_scc0 .LBB0_1119
	s_cmp_lt_u32 s17, 0xffffbb00
	s_cbranch_scc0 .LBB0_1120
	s_cmpk_gt_u32 s33, 0x4fff
	s_cbranch_scc0 .LBB0_1121
	s_cmpk_gt_u32 s33, 0x65ff
	s_mov_b64 s[10:11], -1
	s_cbranch_scc0 .LBB0_1122
	v_readlane_b32 s36, v253, 32
	v_readlane_b32 s37, v253, 33
	v_readlane_b32 s38, v253, 34
	v_readlane_b32 s39, v253, 35
	s_mov_b64 s[0:1], s[36:37]
	s_add_i32 s16, s17, 0xffffdf00
	s_mov_b64 s[2:3], s[38:39]
	s_add_u32 s2, s0, 0x5800000
	s_addc_u32 s3, s1, 0
	s_add_u32 s4, s88, 0xe000000
	v_readlane_b32 s40, v253, 36
	v_readlane_b32 s41, v253, 37
	v_readlane_b32 s42, v253, 38
	v_readlane_b32 s43, v253, 39
	v_readlane_b32 s44, v253, 40
	v_readlane_b32 s45, v253, 41
	v_readlane_b32 s46, v253, 42
	v_readlane_b32 s47, v253, 43
	v_readlane_b32 s48, v253, 44
	v_readlane_b32 s49, v253, 45
	v_readlane_b32 s50, v253, 46
	v_readlane_b32 s51, v253, 47
	s_addc_u32 s5, s89, 0
	s_mov_b64 s[0:1], 0
	s_branch .LBB0_1123

; #define LDS_WAIT() asm volatile("s_waitcnt lgkmcnt(0)" ::: "memory")
; __device__ __forceinline__ TrItem p0_item_of(const Params& p, int it, int lane) {
;     ...
;     if (r < TR_FI) TR_FFN_IN(0)
;     else if ((r -= TR_FI) < TR_FO) TR_FFN_OUT(0)
;     else if ((r -= TR_FO) < TR_IN) { W = p.in[IN_EWI]; WT = (bf16*)(p.ws + WS_WEI); K = D; N = D_EIN; map = 2; }
;     else if ((r -= TR_IN) < TR_OUT) { W = p.in[IN_EWO]; WT = (bf16*)(p.ws + WS_WEO); K = D; N = D; map = 0; }
;     else if ((r -= TR_OUT) < TR_FI) TR_FFN_IN(1)
;     else if ((r -= TR_FI) < TR_FO) TR_FFN_OUT(1)
;     else if ((r -= TR_FO) < TR_FI) TR_FFN_IN(2)
;     else if ((r -= TR_FI) < TR_FO) TR_FFN_OUT(2)
;     else if ((r -= TR_FO) < TR_IN) { W = p.in[IN_OWI]; WT = (bf16*)(p.ws + WS_WOI); K = D; N = D_OIN; map = 3; }
;     else if ((r -= TR_IN) < TR_OUT) { W = p.in[IN_OWO]; WT = (bf16*)(p.ws + WS_WOO); K = D; N = D; map = 0; }
;     else if ((r -= TR_OUT) < TR_FI) TR_FFN_IN(3)
;     else { r -= TR_FI; TR_FFN_OUT(3) }
; __device__ __forceinline__ void tr_range(const Params& p, LAS unsigned char* lds, int first, int stride, int end, int lane, int wave) {
;     ...
;     for (int it = first; it < end; it += stride) {
; #pragma unroll
;         for (int i = 0; i < 64; ++i) scr[i * 65 + lane] = ra[i];
;         const bool more = it + stride < end;
;         TrItem nxt = cur;
;         if (more) { nxt = p0_item_of(p, it + stride, lane);
; #pragma unroll
;             for (int i = 0; i < 64; ++i) ra[i] = nxt.src[(size_t)i * nxt.N]; }
;         LDS_WAIT(); asm volatile("" ::: "memory");
.LBB0_1164:
	s_waitcnt lgkmcnt(0)
	s_add_i32 s46, s46, s43
	s_add_i32 s0, s47, s46
	s_cmpk_lt_i32 s0, 0x6600
	s_mov_b32 s44, s50
	s_mov_b32 s42, s49
	s_mov_b64 s[2:3], s[30:31]
	s_cbranch_scc0 .LBB0_1210
.LBB0_1165:
	v_add_u32_e32 v29, 0x400, v3
	s_waitcnt vmcnt(0)
	ds_write2_b32 v3, v15, v19 offset1:65
	ds_write2_b32 v3, v21, v23 offset0:130 offset1:195
	ds_write2_b32 v29, v25, v30 offset0:4 offset1:69
	ds_write2_b32 v29, v32, v37 offset0:134 offset1:199
	v_add_u32_e32 v29, 0x800, v3
	ds_write2_b32 v29, v40, v27 offset0:8 offset1:73
	ds_write2_b32 v29, v31, v33 offset0:138 offset1:203
	v_add_u32_e32 v29, 0xc00, v3
	ds_write2_b32 v29, v34, v36 offset0:12 offset1:77
	ds_write2_b32 v29, v39, v46 offset0:142 offset1:207
	v_add_u32_e32 v29, 0x1000, v3
	ds_write2_b32 v29, v49, v35 offset0:16 offset1:81
	ds_write2_b32 v29, v38, v41 offset0:146 offset1:211
	v_add_u32_e32 v29, 0x1400, v3
	ds_write2_b32 v29, v42, v44 offset0:20 offset1:85
	ds_write2_b32 v29, v47, v54 offset0:150 offset1:215
	v_add_u32_e32 v29, 0x1800, v3
	ds_write2_b32 v29, v57, v43 offset0:24 offset1:89
	ds_write2_b32 v29, v45, v48 offset0:154 offset1:219
	v_add_u32_e32 v29, 0x1c00, v3
	ds_write2_b32 v29, v50, v52 offset0:28 offset1:93
	ds_write2_b32 v29, v55, v62 offset0:158 offset1:223
	v_add_u32_e32 v29, 0x2000, v3
	ds_write2_b32 v29, v65, v51 offset0:32 offset1:97
	ds_write2_b32 v29, v53, v56 offset0:162 offset1:227
	v_add_u32_e32 v29, 0x2400, v3
	ds_write2_b32 v29, v58, v60 offset0:36 offset1:101
	ds_write2_b32 v29, v63, v70 offset0:166 offset1:231
	v_add_u32_e32 v29, 0x2800, v3
	ds_write2_b32 v29, v73, v59 offset0:40 offset1:105
	ds_write2_b32 v29, v61, v64 offset0:170 offset1:235
	v_add_u32_e32 v29, 0x2c00, v3
	ds_write2_b32 v29, v66, v68 offset0:44 offset1:109
	ds_write2_b32 v29, v71, v76 offset0:174 offset1:239
	v_add_u32_e32 v29, 0x3000, v3
	ds_write2_b32 v29, v78, v67 offset0:48 offset1:113
	ds_write2_b32 v29, v69, v72 offset0:178 offset1:243
	v_add_u32_e32 v29, 0x3400, v3
	s_add_i32 s0, s45, s46
	ds_write2_b32 v29, v74, v75 offset0:52 offset1:117
	ds_write2_b32 v29, v77, v79 offset0:182 offset1:247
	v_add_u32_e32 v29, 0x3800, v3
	s_add_i32 s33, s33, s43
	s_add_i32 s69, s0, 0x4500
	ds_write2_b32 v29, v80, v17 offset0:56 offset1:121
	ds_write2_b32 v29, v81, v82 offset0:186 offset1:251
	v_add_u32_e32 v29, 0x3c00, v3
	s_cmpk_gt_i32 s69, 0x65ff
	ds_write2_b32 v29, v83, v84 offset0:60 offset1:125
	ds_write2_b32 v29, v85, v28 offset0:190 offset1:255
	s_cbranch_scc1 .LBB0_1207
	s_cmpk_lt_i32 s69, 0x1600
	s_cbranch_scc1 .LBB0_1176
	s_cmpk_gt_u32 s69, 0x20ff
	s_cbranch_scc0 .LBB0_1177
	s_cmpk_gt_u32 s69, 0x2aff
	s_cbranch_scc0 .LBB0_1178
	s_cmpk_gt_u32 s69, 0x2eff
	s_cbranch_scc0 .LBB0_1179
	s_cmpk_gt_u32 s69, 0x44ff
	s_mov_b64 s[40:41], -1
	s_cbranch_scc0 .LBB0_1184
	s_cmpk_gt_u32 s69, 0x4fff
	s_cbranch_scc0 .LBB0_1181
	s_mov_b64 s[36:37], -1
	s_cmpk_gt_u32 s69, 0x65ff
	s_mov_b64 s[30:31], -1
	s_cbranch_scc0 .LBB0_1174
	s_add_i32 s68, s0, 0xffffdf00
	s_mov_b64 s[30:31], 0

; #define LAS __attribute__((address_space(3)))
; __device__ __forceinline__ TrItem p0_item_of(const Params& p, int it, int lane) {
;     const float* W; bf16* WT; int K, N, map, r = it, f8 = 0;
;     ...
;     if (r < TR_FI) TR_FFN_IN(0)
;     else if ((r -= TR_FI) < TR_FO) TR_FFN_OUT(0)
;     else if ((r -= TR_FO) < TR_IN) { W = p.in[IN_EWI]; WT = (bf16*)(p.ws + WS_WEI); K = D; N = D_EIN; map = 2; }
;     else if ((r -= TR_IN) < TR_OUT) { W = p.in[IN_EWO]; WT = (bf16*)(p.ws + WS_WEO); K = D; N = D; map = 0; }
;     else if ((r -= TR_OUT) < TR_FI) TR_FFN_IN(1)
;     else if ((r -= TR_FI) < TR_FO) TR_FFN_OUT(1)
;     else if ((r -= TR_FO) < TR_FI) TR_FFN_IN(2)
;     else if ((r -= TR_FI) < TR_FO) TR_FFN_OUT(2)
;     else if ((r -= TR_FO) < TR_IN) { W = p.in[IN_OWI]; WT = (bf16*)(p.ws + WS_WOI); K = D; N = D_OIN; map = 3; }
;     else if ((r -= TR_IN) < TR_OUT) { W = p.in[IN_OWO]; WT = (bf16*)(p.ws + WS_WOO); K = D; N = D; map = 0; }
;     else if ((r -= TR_OUT) < TR_FI) TR_FFN_IN(3)
;     else { r -= TR_FI; TR_FFN_OUT(3) }
;     ...
;     const int nblk = N / 64, kb = r / nblk, nb = r % nblk, k0 = 64 * kb, n0 = 64 * nb;
; __device__ __forceinline__ void tail_convert(const Params& p, LAS unsigned char* lds, int slot, int units, int lane, int wave) {
;     const int G = gridDim.x, c = blockIdx.x, rem = units % G;
;     if (rem != 0 && c < rem) return;
;     const int nw = rem ? G - rem : G, j = rem ? c - rem : c;
;     tr_range(p, lds, TR_SLOT[slot] + j * 8 + wave, nw * 8, TR_SLOT[slot + 1], lane, wave);
.LBB0_1455:
	s_abs_i32 s0, s97
	v_cvt_f32_u32_e32 v2, s0
	s_sub_i32 s1, 0, s0
	v_rcp_iflag_f32_e32 v2, v2
	s_nop 0
	v_mul_f32_e32 v2, 0x4f7ffffe, v2
	v_cvt_u32_f32_e32 v2, v2
	s_nop 0
	v_readfirstlane_b32 s2, v2
	s_mul_i32 s1, s1, s2
	s_mul_hi_u32 s1, s2, s1
	s_add_i32 s2, s2, s1
	s_mul_hi_u32 s1, s2, 0xc60
	s_mul_i32 s1, s1, s0
	s_sub_i32 s1, 0xc60, s1
	s_sub_i32 s2, s1, s0
	s_cmp_ge_u32 s1, s0
	s_cselect_b32 s1, s2, s1
	s_sub_i32 s2, s1, s0
	s_cmp_ge_u32 s1, s0
	s_cselect_b32 s46, s2, s1
	s_cmp_lg_u32 s46, 0
	s_cselect_b64 s[0:1], -1, 0
	s_cmp_lt_i32 s86, s46
	s_cselect_b64 s[2:3], -1, 0
	s_and_b64 s[0:1], s[0:1], s[2:3]
	s_and_b64 vcc, exec, s[0:1]
	s_cbranch_vccnz .LBB0_1602
	s_sub_i32 s0, s86, s46
	s_addk_i32 s0, 0xfea0
	s_lshl_b32 s18, s0, 3
	s_add_i32 s18, s18, s96
	s_add_i32 s33, s18, 0x7100
	s_cmp_gt_i32 s33, 0x8dff
	s_cbranch_scc1 .LBB0_1602
	s_cmpk_gt_i32 s33, 0x15ff
	v_writelane_b32 v252, s76, 24
	s_cbranch_scc0 .LBB0_1469
	s_cmpk_gt_u32 s33, 0x20ff
	s_cbranch_scc0 .LBB0_1470
	s_cmpk_gt_u32 s33, 0x2aff
	s_cbranch_scc0 .LBB0_1471
	s_cmpk_gt_u32 s33, 0x2eff
	s_cbranch_scc0 .LBB0_1472
	s_cmpk_gt_u32 s33, 0x44ff
	s_cbranch_scc0 .LBB0_1473
	s_cmpk_gt_u32 s33, 0x4fff
	s_cbranch_scc0 .LBB0_1474
	s_cmpk_gt_u32 s33, 0x65ff
	s_cbranch_scc0 .LBB0_1475
	s_cmp_lt_u32 s18, 0xffff8f00
	s_cbranch_scc0 .LBB0_1476
	s_cmpk_gt_u32 s33, 0x7aff
	s_cbranch_scc0 .LBB0_1477
	s_cmpk_gt_u32 s33, 0x7eff
	s_cbranch_scc0 .LBB0_1478
	s_cmpk_gt_u32 s33, 0x94ff
	s_mov_b64 s[10:11], -1
	s_cbranch_scc0 .LBB0_1479
	v_readlane_b32 s68, v253, 32
	v_readlane_b32 s69, v253, 33
	v_readlane_b32 s70, v253, 34
	v_readlane_b32 s71, v253, 35
	s_mov_b64 s[0:1], s[68:69]
	s_add_i32 s19, s18, 0xffffdc00
	s_mov_b64 s[2:3], s[70:71]
	s_add_u32 s2, s0, 0x8400000
	s_addc_u32 s3, s1, 0
	s_add_u32 s4, s88, 0xf600000
	v_readlane_b32 s72, v253, 36
	v_readlane_b32 s73, v253, 37
	v_readlane_b32 s74, v253, 38
	v_readlane_b32 s75, v253, 39
	v_readlane_b32 s76, v253, 40
	v_readlane_b32 s77, v253, 41
	v_readlane_b32 s78, v253, 42
	v_readlane_b32 s79, v253, 43
	v_readlane_b32 s80, v253, 44
	v_readlane_b32 s81, v253, 45
	v_readlane_b32 s82, v253, 46
	v_readlane_b32 s83, v253, 47
	s_addc_u32 s5, s89, 0
	s_mov_b64 s[0:1], 0
	s_branch .LBB0_1480

; #define LAS __attribute__((address_space(3)))
; __device__ __forceinline__ TrItem p0_item_of(const Params& p, int it, int lane) {
;     ...
;     const int nblk = N / 64, kb = r / nblk, nb = r % nblk, k0 = 64 * kb, n0 = 64 * nb;
;     TrItem t; t.src = W + (size_t)k0 * N + srccol(map, n0 + lane); t.N = N; t.K = K; t.fp8 = f8;
;     t.dst = f8 ? (bf16*)((unsigned char*)WT + (size_t)n0 * K + k0) : WT + (size_t)n0 * K + k0; return t;
; }
; __device__ __forceinline__ void tr_range(const Params& p, LAS unsigned char* lds, int first, int stride, int end, int lane, int wave) {
;     LAS float* scr = (LAS float*)(lds + wave * (64 * 65 * 4));
;     if (first >= end) return;
;     float ra[64];
;     TrItem cur = p0_item_of(p, first, lane);
; #pragma unroll
;     for (int i = 0; i < 64; ++i) ra[i] = cur.src[(size_t)i * cur.N];
.LBB0_1532:
	s_lshl_b32 s16, s21, 6
	s_ashr_i32 s17, s16, 31
	s_mul_i32 s11, s17, s0
	s_mul_hi_u32 s18, s16, s0
	s_sub_i32 s1, s97, s46
	s_mul_i32 s10, s96, 0x4100
	s_add_i32 s19, s18, s11
	s_mul_i32 s18, s16, s0
	s_lshl_b32 s78, s1, 3
	s_add_i32 s10, s10, 0
	s_lshl_b64 s[18:19], s[18:19], 2
	s_add_u32 s2, s2, s18
	s_addc_u32 s3, s3, s19
	v_ashrrev_i32_e32 v3, 31, v2
	v_lshl_add_u64 v[2:3], v[2:3], 2, s[2:3]
	s_ashr_i32 s2, s20, 31
	s_mul_hi_u32 s3, s20, s74
	s_mul_i32 s2, s2, s74
	s_add_i32 s3, s3, s2
	s_mul_i32 s2, s20, s74
	s_lshl_b64 s[18:19], s[2:3], 1
	s_add_u32 s11, s4, s18
	s_addc_u32 s20, s5, s19
	s_lshl_b64 s[18:19], s[16:17], 1
	s_add_u32 s11, s11, s18
	s_addc_u32 s18, s20, s19
	s_add_u32 s2, s4, s2
	s_addc_u32 s3, s5, s3
	s_add_u32 s4, s2, s16
	s_addc_u32 s5, s3, s17
	s_mov_b32 s1, 0
	s_and_b64 s[2:3], s[8:9], exec
	s_cselect_b32 s3, s18, s5
	s_cselect_b32 s2, s11, s4
	s_mul_i32 s4, s0, 63
	s_mov_b32 s5, s1
	v_lshl_add_u64 v[4:5], s[4:5], 2, v[2:3]
	s_mul_i32 s4, s0, 62
	global_load_dword v86, v[4:5], off
	v_lshl_add_u64 v[4:5], s[4:5], 2, v[2:3]
	s_mul_i32 s4, s0, 61
	global_load_dword v59, v[4:5], off
	v_lshl_add_u64 v[4:5], s[4:5], 2, v[2:3]
	s_mul_i32 s4, s0, 60
	global_load_dword v60, v[4:5], off
	v_lshl_add_u64 v[4:5], s[4:5], 2, v[2:3]
	s_mul_i32 s4, s0, 59
	global_load_dword v61, v[4:5], off
	v_lshl_add_u64 v[4:5], s[4:5], 2, v[2:3]
	s_mul_i32 s4, s0, 58
	global_load_dword v62, v[4:5], off
	v_lshl_add_u64 v[4:5], s[4:5], 2, v[2:3]
	s_mul_i32 s4, s0, 57
	global_load_dword v63, v[4:5], off
	v_lshl_add_u64 v[4:5], s[4:5], 2, v[2:3]
	s_mul_i32 s4, s0, 56
	global_load_dword v64, v[4:5], off
	v_lshl_add_u64 v[4:5], s[4:5], 2, v[2:3]
	s_mul_i32 s4, s0, 55
	global_load_dword v65, v[4:5], off
	v_lshl_add_u64 v[4:5], s[4:5], 2, v[2:3]
	s_mul_i32 s4, s0, 54
	global_load_dword v72, v[4:5], off
	v_lshl_add_u64 v[4:5], s[4:5], 2, v[2:3]
	s_mul_i32 s4, s0, 53
	global_load_dword v15, v[4:5], off
	v_lshl_add_u64 v[4:5], s[4:5], 2, v[2:3]
	s_mul_i32 s4, s0, 52
	global_load_dword v17, v[4:5], off
	v_lshl_add_u64 v[4:5], s[4:5], 2, v[2:3]
	s_mul_i32 s4, s0, 51
	global_load_dword v19, v[4:5], off
	v_lshl_add_u64 v[4:5], s[4:5], 2, v[2:3]
	s_mul_i32 s4, s0, 50
	global_load_dword v21, v[4:5], off
	v_lshl_add_u64 v[4:5], s[4:5], 2, v[2:3]
	s_mul_i32 s4, s0, 49
	global_load_dword v23, v[4:5], off
	v_lshl_add_u64 v[4:5], s[4:5], 2, v[2:3]
	s_mul_i32 s4, s0, 48
	global_load_dword v73, v[4:5], off
	v_lshl_add_u64 v[4:5], s[4:5], 2, v[2:3]
	s_mul_i32 s4, s0, 47
	global_load_dword v66, v[4:5], off
	v_lshl_add_u64 v[4:5], s[4:5], 2, v[2:3]
	s_mul_i32 s4, s0, 46
	global_load_dword v74, v[4:5], off
	v_lshl_add_u64 v[4:5], s[4:5], 2, v[2:3]
	s_mul_i32 s4, s0, 45
	global_load_dword v25, v[4:5], off
	v_lshl_add_u64 v[4:5], s[4:5], 2, v[2:3]
	s_mul_i32 s4, s0, 44
	global_load_dword v27, v[4:5], off
	v_lshl_add_u64 v[4:5], s[4:5], 2, v[2:3]
	s_mul_i32 s4, s0, 43
	global_load_dword v30, v[4:5], off
	v_lshl_add_u64 v[4:5], s[4:5], 2, v[2:3]
	s_mul_i32 s4, s0, 42
	global_load_dword v31, v[4:5], off
	v_lshl_add_u64 v[4:5], s[4:5], 2, v[2:3]
	s_mul_i32 s4, s0, 41
	global_load_dword v32, v[4:5], off
	v_lshl_add_u64 v[4:5], s[4:5], 2, v[2:3]
	s_mul_i32 s4, s0, 40
	global_load_dword v75, v[4:5], off
	v_lshl_add_u64 v[4:5], s[4:5], 2, v[2:3]
	s_mul_i32 s4, s0, 39
	global_load_dword v67, v[4:5], off
	v_lshl_add_u64 v[4:5], s[4:5], 2, v[2:3]
	s_mul_i32 s4, s0, 38
	global_load_dword v76, v[4:5], off
	v_lshl_add_u64 v[4:5], s[4:5], 2, v[2:3]
	s_mul_i32 s4, s0, 37
	global_load_dword v33, v[4:5], off
	v_lshl_add_u64 v[4:5], s[4:5], 2, v[2:3]
	s_mul_i32 s4, s0, 36
	global_load_dword v34, v[4:5], off
	v_lshl_add_u64 v[4:5], s[4:5], 2, v[2:3]
	s_mul_i32 s4, s0, 35
	global_load_dword v35, v[4:5], off
	v_lshl_add_u64 v[4:5], s[4:5], 2, v[2:3]
	s_mul_i32 s4, s0, 34
	global_load_dword v36, v[4:5], off
	v_lshl_add_u64 v[4:5], s[4:5], 2, v[2:3]
	s_mul_i32 s4, s0, 33
	global_load_dword v37, v[4:5], off
	v_lshl_add_u64 v[4:5], s[4:5], 2, v[2:3]
	s_lshl_b32 s4, s0, 5
	global_load_dword v77, v[4:5], off
	v_lshl_add_u64 v[4:5], s[4:5], 2, v[2:3]
	s_mul_i32 s4, s0, 31
	global_load_dword v68, v[4:5], off
	v_lshl_add_u64 v[4:5], s[4:5], 2, v[2:3]
	s_mul_i32 s4, s0, 30
	global_load_dword v78, v[4:5], off
	v_lshl_add_u64 v[4:5], s[4:5], 2, v[2:3]
	s_mul_i32 s4, s0, 29
	global_load_dword v38, v[4:5], off
	v_lshl_add_u64 v[4:5], s[4:5], 2, v[2:3]
	s_mul_i32 s4, s0, 28
	global_load_dword v39, v[4:5], off
	v_lshl_add_u64 v[4:5], s[4:5], 2, v[2:3]
	s_mul_i32 s4, s0, 27
	global_load_dword v40, v[4:5], off
	v_lshl_add_u64 v[4:5], s[4:5], 2, v[2:3]
	s_mul_i32 s4, s0, 26
	global_load_dword v41, v[4:5], off
	v_lshl_add_u64 v[4:5], s[4:5], 2, v[2:3]
	s_mul_i32 s4, s0, 25
	global_load_dword v42, v[4:5], off
	v_lshl_add_u64 v[4:5], s[4:5], 2, v[2:3]
	s_mul_i32 s4, s0, 24
	global_load_dword v79, v[4:5], off
	v_lshl_add_u64 v[4:5], s[4:5], 2, v[2:3]
	s_mul_i32 s4, s0, 23
	global_load_dword v69, v[4:5], off
	v_lshl_add_u64 v[4:5], s[4:5], 2, v[2:3]
	s_mul_i32 s4, s0, 22
	global_load_dword v80, v[4:5], off
	v_lshl_add_u64 v[4:5], s[4:5], 2, v[2:3]
	s_mul_i32 s4, s0, 21
	global_load_dword v43, v[4:5], off
	v_lshl_add_u64 v[4:5], s[4:5], 2, v[2:3]
	s_mul_i32 s4, s0, 20
	global_load_dword v44, v[4:5], off
	v_lshl_add_u64 v[4:5], s[4:5], 2, v[2:3]
	s_mul_i32 s4, s0, 19
; __device__ __forceinline__ unsigned cvt_pk_bf16(float lo, float hi) { unsigned r; asm volatile("v_cvt_pk_bf16_f32 %0, %1, %2" : "=v"(r) : "v"(lo), "v"(hi)); return r; }
; #define LAS __attribute__((address_space(3)))
; #define LDS_WAIT() asm volatile("s_waitcnt lgkmcnt(0)" ::: "memory")
; __device__ __forceinline__ void tr_range(const Params& p, LAS unsigned char* lds, int first, int stride, int end, int lane, int wave) {
;     LAS float* scr = (LAS float*)(lds + wave * (64 * 65 * 4));
;     if (first >= end) return;
;     float ra[64];
;     TrItem cur = p0_item_of(p, first, lane);
; #pragma unroll
;     for (int i = 0; i < 64; ++i) ra[i] = cur.src[(size_t)i * cur.N];
; #pragma unroll 1
;     for (int it = first; it < end; it += stride) {
; #pragma unroll
;         for (int i = 0; i < 64; ++i) scr[i * 65 + lane] = ra[i];
;         const bool more = it + stride < end;
;         TrItem nxt = cur;
;         if (more) { nxt = p0_item_of(p, it + stride, lane);
; #pragma unroll
;             for (int i = 0; i < 64; ++i) ra[i] = nxt.src[(size_t)i * nxt.N]; }
;         LDS_WAIT(); asm volatile("" ::: "memory");
;         if (cur.fp8) {
;             const int c = lane & 3;
; #pragma unroll
;             for (int j = 0; j < 4; ++j) { const int n = (lane >> 2) + 16 * j; const LAS float* s = scr + (16 * c) * 65 + n;
;                 u32x4 o;
;                 o.x = pk4_fp8(s[0 * 65] * W8_SCALE, s[1 * 65] * W8_SCALE, s[2 * 65] * W8_SCALE, s[3 * 65] * W8_SCALE);
;                 o.y = pk4_fp8(s[4 * 65] * W8_SCALE, s[5 * 65] * W8_SCALE, s[6 * 65] * W8_SCALE, s[7 * 65] * W8_SCALE);
;                 o.z = pk4_fp8(s[8 * 65] * W8_SCALE, s[9 * 65] * W8_SCALE, s[10 * 65] * W8_SCALE, s[11 * 65] * W8_SCALE);
;                 o.w = pk4_fp8(s[12 * 65] * W8_SCALE, s[13 * 65] * W8_SCALE, s[14 * 65] * W8_SCALE, s[15 * 65] * W8_SCALE);
;                 *(u32x4*)((unsigned char*)cur.dst + (size_t)n * cur.K + 16 * c) = o; }
;         } else {
;         const int c = lane & 7;
; #pragma unroll
;         for (int j = 0; j < 8; ++j) { const int n = (lane >> 3) + 8 * j; const LAS float* s = scr + (8 * c) * 65 + n;
;             u32x4 o; o.x = pg8::cvt_pk_bf16(s[0 * 65], s[1 * 65]); o.y = pg8::cvt_pk_bf16(s[2 * 65], s[3 * 65]); o.z = pg8::cvt_pk_bf16(s[4 * 65], s[5 * 65]); o.w = pg8::cvt_pk_bf16(s[6 * 65], s[7 * 65]);
	global_load_dword v45, v[4:5], off
	v_lshl_add_u64 v[4:5], s[4:5], 2, v[2:3]
	s_mul_i32 s4, s0, 18
	global_load_dword v46, v[4:5], off
	v_lshl_add_u64 v[4:5], s[4:5], 2, v[2:3]
	s_mul_i32 s4, s0, 17
	global_load_dword v47, v[4:5], off
	v_lshl_add_u64 v[4:5], s[4:5], 2, v[2:3]
	s_lshl_b32 s4, s0, 4
	global_load_dword v81, v[4:5], off
	v_lshl_add_u64 v[4:5], s[4:5], 2, v[2:3]
	s_mul_i32 s4, s0, 15
	global_load_dword v70, v[4:5], off
	v_lshl_add_u64 v[4:5], s[4:5], 2, v[2:3]
	s_mul_i32 s4, s0, 14
	global_load_dword v82, v[4:5], off
	v_lshl_add_u64 v[4:5], s[4:5], 2, v[2:3]
	s_mul_i32 s4, s0, 13
	global_load_dword v48, v[4:5], off
	v_lshl_add_u64 v[4:5], s[4:5], 2, v[2:3]
	s_mul_i32 s4, s0, 12
	global_load_dword v49, v[4:5], off
	v_lshl_add_u64 v[4:5], s[4:5], 2, v[2:3]
	s_mul_i32 s4, s0, 11
	global_load_dword v50, v[4:5], off
	v_lshl_add_u64 v[4:5], s[4:5], 2, v[2:3]
	s_mul_i32 s4, s0, 10
	global_load_dword v51, v[4:5], off
	v_lshl_add_u64 v[4:5], s[4:5], 2, v[2:3]
	s_mul_i32 s4, s0, 9
	global_load_dword v52, v[4:5], off
	v_lshl_add_u64 v[4:5], s[4:5], 2, v[2:3]
	s_lshl_b32 s4, s0, 3
	global_load_dword v83, v[4:5], off
	v_lshl_add_u64 v[4:5], s[4:5], 2, v[2:3]
	s_mul_i32 s4, s0, 7
	global_load_dword v71, v[4:5], off
	v_lshl_add_u64 v[4:5], s[4:5], 2, v[2:3]
	s_mul_i32 s4, s0, 6
	global_load_dword v84, v[4:5], off
	v_lshl_add_u64 v[4:5], s[4:5], 2, v[2:3]
	s_mul_i32 s4, s0, 5
	global_load_dword v53, v[4:5], off
	v_lshl_add_u64 v[4:5], s[4:5], 2, v[2:3]
	s_lshl_b32 s4, s0, 2
	global_load_dword v54, v[4:5], off
	v_lshl_add_u64 v[4:5], s[4:5], 2, v[2:3]
	s_mul_i32 s4, s0, 3
	global_load_dword v55, v[4:5], off
	v_lshl_add_u64 v[4:5], s[4:5], 2, v[2:3]
	s_lshl_b32 s4, s0, 1
	global_load_dword v56, v[4:5], off
	v_lshl_add_u64 v[4:5], s[4:5], 2, v[2:3]
	global_load_dword v57, v[4:5], off
	v_lshl_add_u64 v[4:5], s[0:1], 2, v[2:3]
	global_load_dword v58, v[4:5], off
	global_load_dword v85, v[2:3], off
	v_readlane_b32 s16, v253, 32
	v_readlane_b32 s18, v253, 34
	v_readlane_b32 s19, v253, 35
	v_readlane_b32 s17, v253, 33
	s_mov_b64 s[38:39], s[18:19]
	s_mov_b64 s[36:37], s[16:17]
	s_add_u32 s94, s36, 0x8400000
	v_readlane_b32 s20, v253, 36
	v_readlane_b32 s21, v253, 37
	v_readlane_b32 s22, v253, 38
	v_readlane_b32 s23, v253, 39
	v_readlane_b32 s24, v253, 40
	v_readlane_b32 s25, v253, 41
	v_readlane_b32 s26, v253, 42
	v_readlane_b32 s27, v253, 43
	v_readlane_b32 s28, v253, 44
	v_readlane_b32 s29, v253, 45
	v_readlane_b32 s30, v253, 46
	v_readlane_b32 s31, v253, 47
	s_addc_u32 s95, s37, 0
	s_add_u32 s4, s88, 0xf600000
	v_readlane_b32 s16, v253, 10
	s_addc_u32 s5, s89, 0
	v_readlane_b32 s30, v253, 24
	v_readlane_b32 s31, v253, 25
	v_writelane_b32 v252, s4, 14
	v_readlane_b32 s28, v253, 22
	v_readlane_b32 s29, v253, 23
	s_mov_b64 s[50:51], s[30:31]
	v_writelane_b32 v252, s5, 15
	s_add_u32 s4, s50, 0x10800000
	s_addc_u32 s5, s51, 0
	s_add_u32 s76, s88, 0x8800000
	v_writelane_b32 v252, s4, 12
	s_addc_u32 s77, s89, 0
	v_lshlrev_b32_e32 v4, 3, v0
	v_writelane_b32 v252, s5, 13
	s_add_u32 s4, s88, 0x13c00000
	s_addc_u32 s5, s89, 0
	v_lshrrev_b32_e32 v6, 3, v1
	v_and_b32_e32 v4, 56, v4
	s_add_u32 s8, s88, 0x12800000
	v_mul_u32_u24_e32 v8, 0x104, v130
	v_mul_u32_u24_e32 v11, 0x104, v4
	v_and_b32_e32 v9, 60, v1
	v_lshlrev_b32_e32 v13, 2, v6
	s_addc_u32 s9, s89, 0
	v_lshl_add_u32 v3, v1, 2, s10
	v_add3_u32 v9, s10, v8, v9
	v_add3_u32 v11, s10, v11, v13
	s_add_u32 s10, s36, 0x5800000
	s_addc_u32 s11, s37, 0
	v_readlane_b32 s17, v253, 11
	s_add_u32 s16, s88, 0xe000000
	s_addc_u32 s17, s89, 0
	v_writelane_b32 v252, s16, 16
	v_lshrrev_b32_e32 v2, 2, v1
	v_mov_b32_e32 v5, 0
	v_writelane_b32 v252, s17, 17
	s_add_u32 s16, s50, 0xb000000
	s_addc_u32 s17, s51, 0
	v_writelane_b32 v252, s16, 18
	v_and_b32_e32 v7, 31, v0
	v_mov_b32_e32 v131, v5
	v_writelane_b32 v252, s17, 19
	s_add_u32 s16, s36, 0x2c00000
	s_addc_u32 s17, s37, 0
	v_writelane_b32 v252, s16, 22
	v_or_b32_e32 v8, 16, v2
	v_or_b32_e32 v10, 32, v2
	v_writelane_b32 v252, s17, 23
	s_add_u32 s16, s88, 0xca00000
	s_addc_u32 s17, s89, 0
	s_add_u32 s34, s50, 0x5800000
	s_addc_u32 s35, s51, 0
	s_add_u32 s36, s88, 0x3000000
	s_addc_u32 s37, s89, 0
	s_add_u32 s38, s88, 0x12000000
	s_addc_u32 s39, s89, 0
	s_add_u32 s40, s88, 0x10c00000
	s_addc_u32 s41, s89, 0
	s_add_u32 s42, s88, 0xb400000
	s_addc_u32 s43, s89, 0
	s_add_u32 s44, s88, 0x400000
	s_addc_u32 s45, s89, 0
	s_lshl_b32 s0, s97, 3
	s_lshl_b32 s47, s46, 4
	s_sub_i32 s79, s0, s47
	s_lshl_b32 s0, s86, 3
	s_addk_i32 s0, 0xf500
	s_add_i32 s80, s96, s0
	s_lshl_b32 s0, s46, 3
	v_or_b32_e32 v12, 48, v2
	v_or_b32_e32 v14, 8, v6
	v_or_b32_e32 v16, 16, v6
	v_or_b32_e32 v18, 24, v6
	v_or_b32_e32 v20, 32, v6
	v_or_b32_e32 v22, 40, v6
	v_or_b32_e32 v24, 48, v6
	v_or_b32_e32 v26, 56, v6
	v_writelane_b32 v252, s16, 20
	s_sub_i32 s81, 0x7100, s0
	s_mov_b32 s82, 0xc3e00000
	v_lshlrev_b32_e32 v4, 1, v4
	v_mov_b32_e32 v13, 0x43e00000
	s_mov_b32 s88, s75
	s_mov_b64 s[46:47], s[2:3]
	s_mov_b32 s83, s74
	v_readlane_b32 s18, v253, 12
	v_readlane_b32 s19, v253, 13
	v_readlane_b32 s20, v253, 14
	v_readlane_b32 s21, v253, 15
	v_readlane_b32 s22, v253, 16
	v_readlane_b32 s23, v253, 17
	v_readlane_b32 s24, v253, 18
	v_readlane_b32 s25, v253, 19
	v_readlane_b32 s26, v253, 20
	v_readlane_b32 s27, v253, 21
	s_mov_b64 s[48:49], s[28:29]
	v_writelane_b32 v252, s17, 21
	s_branch .LBB0_1535

; #define LDS_WAIT() asm volatile("s_waitcnt lgkmcnt(0)" ::: "memory")
; __device__ __forceinline__ TrItem p0_item_of(const Params& p, int it, int lane) {
;     ...
;     if (r < TR_FI) TR_FFN_IN(0)
;     else if ((r -= TR_FI) < TR_FO) TR_FFN_OUT(0)
;     else if ((r -= TR_FO) < TR_IN) { W = p.in[IN_EWI]; WT = (bf16*)(p.ws + WS_WEI); K = D; N = D_EIN; map = 2; }
;     else if ((r -= TR_IN) < TR_OUT) { W = p.in[IN_EWO]; WT = (bf16*)(p.ws + WS_WEO); K = D; N = D; map = 0; }
;     else if ((r -= TR_OUT) < TR_FI) TR_FFN_IN(1)
;     else if ((r -= TR_FI) < TR_FO) TR_FFN_OUT(1)
;     else if ((r -= TR_FO) < TR_FI) TR_FFN_IN(2)
;     else if ((r -= TR_FI) < TR_FO) TR_FFN_OUT(2)
;     else if ((r -= TR_FO) < TR_IN) { W = p.in[IN_OWI]; WT = (bf16*)(p.ws + WS_WOI); K = D; N = D_OIN; map = 3; }
;     else if ((r -= TR_IN) < TR_OUT) { W = p.in[IN_OWO]; WT = (bf16*)(p.ws + WS_WOO); K = D; N = D; map = 0; }
;     else if ((r -= TR_OUT) < TR_FI) TR_FFN_IN(3)
;     else { r -= TR_FI; TR_FFN_OUT(3) }
; __device__ __forceinline__ void tr_range(const Params& p, LAS unsigned char* lds, int first, int stride, int end, int lane, int wave) {
;     ...
;     for (int it = first; it < end; it += stride) {
; #pragma unroll
;         for (int i = 0; i < 64; ++i) scr[i * 65 + lane] = ra[i];
;         const bool more = it + stride < end;
;         TrItem nxt = cur;
;         if (more) { nxt = p0_item_of(p, it + stride, lane);
; #pragma unroll
;             for (int i = 0; i < 64; ++i) ra[i] = nxt.src[(size_t)i * nxt.N]; }
;         LDS_WAIT(); asm volatile("" ::: "memory");
.LBB0_1534:
	s_waitcnt lgkmcnt(0)
	s_add_i32 s80, s80, s78
	s_add_i32 s0, s81, s80
	s_cmp_lt_i32 s0, 0x8e00
	s_mov_b32 s75, s88
	s_mov_b32 s74, s83
	s_mov_b64 s[2:3], s[46:47]
	s_cbranch_scc0 .LBB0_1601
.LBB0_1535:
	v_add_u32_e32 v28, 0x400, v3
	s_waitcnt vmcnt(0)
	ds_write2_b32 v3, v85, v58 offset1:65
	ds_write2_b32 v3, v57, v56 offset0:130 offset1:195
	ds_write2_b32 v28, v55, v54 offset0:4 offset1:69
	ds_write2_b32 v28, v53, v84 offset0:134 offset1:199
	v_add_u32_e32 v28, 0x800, v3
	ds_write2_b32 v28, v71, v83 offset0:8 offset1:73
	ds_write2_b32 v28, v52, v51 offset0:138 offset1:203
	v_add_u32_e32 v28, 0xc00, v3
	ds_write2_b32 v28, v50, v49 offset0:12 offset1:77
	ds_write2_b32 v28, v48, v82 offset0:142 offset1:207
	v_add_u32_e32 v28, 0x1000, v3
	ds_write2_b32 v28, v70, v81 offset0:16 offset1:81
	ds_write2_b32 v28, v47, v46 offset0:146 offset1:211
	v_add_u32_e32 v28, 0x1400, v3
	ds_write2_b32 v28, v45, v44 offset0:20 offset1:85
	ds_write2_b32 v28, v43, v80 offset0:150 offset1:215
	v_add_u32_e32 v28, 0x1800, v3
	ds_write2_b32 v28, v69, v79 offset0:24 offset1:89
	ds_write2_b32 v28, v42, v41 offset0:154 offset1:219
	v_add_u32_e32 v28, 0x1c00, v3
	ds_write2_b32 v28, v40, v39 offset0:28 offset1:93
	ds_write2_b32 v28, v38, v78 offset0:158 offset1:223
	v_add_u32_e32 v28, 0x2000, v3
	ds_write2_b32 v28, v68, v77 offset0:32 offset1:97
	ds_write2_b32 v28, v37, v36 offset0:162 offset1:227
	v_add_u32_e32 v28, 0x2400, v3
	ds_write2_b32 v28, v35, v34 offset0:36 offset1:101
	ds_write2_b32 v28, v33, v76 offset0:166 offset1:231
	v_add_u32_e32 v28, 0x2800, v3
	ds_write2_b32 v28, v67, v75 offset0:40 offset1:105
	ds_write2_b32 v28, v32, v31 offset0:170 offset1:235
	v_add_u32_e32 v28, 0x2c00, v3
	ds_write2_b32 v28, v30, v27 offset0:44 offset1:109
	ds_write2_b32 v28, v25, v74 offset0:174 offset1:239
	v_add_u32_e32 v28, 0x3000, v3
	ds_write2_b32 v28, v66, v73 offset0:48 offset1:113
	ds_write2_b32 v28, v23, v21 offset0:178 offset1:243
	v_add_u32_e32 v28, 0x3400, v3
	s_add_i32 s0, s79, s80
	ds_write2_b32 v28, v19, v17 offset0:52 offset1:117
	ds_write2_b32 v28, v15, v72 offset0:182 offset1:247
	v_add_u32_e32 v28, 0x3800, v3
	s_add_i32 s33, s33, s78
	s_add_i32 s73, s0, 0x7100
	ds_write2_b32 v28, v65, v64 offset0:56 offset1:121
	ds_write2_b32 v28, v63, v62 offset0:186 offset1:251
	v_add_u32_e32 v28, 0x3c00, v3
	s_cmp_gt_i32 s73, 0x8dff
	ds_write2_b32 v28, v61, v60 offset0:60 offset1:125
	ds_write2_b32 v28, v59, v86 offset0:190 offset1:255
	s_cbranch_scc1 .LBB0_1598
	s_cmpk_lt_i32 s73, 0x1600
	s_cbranch_scc1 .LBB0_1550
	s_cmpk_gt_u32 s73, 0x20ff
	s_cbranch_scc0 .LBB0_1551
	s_cmpk_gt_u32 s73, 0x2aff
	s_cbranch_scc0 .LBB0_1552
	s_cmpk_gt_u32 s73, 0x2eff
	s_cbranch_scc0 .LBB0_1553
	s_cmpk_gt_u32 s73, 0x44ff
	s_mov_b64 s[70:71], -1
	s_cbranch_scc0 .LBB0_1572
	s_cmpk_gt_u32 s73, 0x4fff
	s_cbranch_scc0 .LBB0_1569
	s_cmpk_gt_u32 s73, 0x65ff
	s_cbranch_scc0 .LBB0_1566
	s_cmpk_gt_u32 s73, 0x70ff
	s_cbranch_scc0 .LBB0_1563
	s_cmpk_gt_u32 s73, 0x7aff
	s_cbranch_scc0 .LBB0_1554
	s_cmpk_gt_u32 s73, 0x7eff
	s_cbranch_scc0 .LBB0_1555
	s_mov_b64 s[68:69], -1
	s_cmpk_gt_u32 s73, 0x94ff
	s_mov_b64 s[46:47], -1
	s_cbranch_scc0 .LBB0_1548
	s_add_i32 s72, s0, 0xffffdc00
	s_mov_b64 s[46:47], 0

; #define LAS __attribute__((address_space(3)))
; __device__ __forceinline__ TrItem p0_item_of(const Params& p, int it, int lane) {
;     const float* W; bf16* WT; int K, N, map, r = it, f8 = 0;
;     ...
;     if (r < TR_FI) TR_FFN_IN(0)
;     else if ((r -= TR_FI) < TR_FO) TR_FFN_OUT(0)
;     else if ((r -= TR_FO) < TR_IN) { W = p.in[IN_EWI]; WT = (bf16*)(p.ws + WS_WEI); K = D; N = D_EIN; map = 2; }
;     else if ((r -= TR_IN) < TR_OUT) { W = p.in[IN_EWO]; WT = (bf16*)(p.ws + WS_WEO); K = D; N = D; map = 0; }
;     else if ((r -= TR_OUT) < TR_FI) TR_FFN_IN(1)
;     else if ((r -= TR_FI) < TR_FO) TR_FFN_OUT(1)
;     else if ((r -= TR_FO) < TR_FI) TR_FFN_IN(2)
;     else if ((r -= TR_FI) < TR_FO) TR_FFN_OUT(2)
;     else if ((r -= TR_FO) < TR_IN) { W = p.in[IN_OWI]; WT = (bf16*)(p.ws + WS_WOI); K = D; N = D_OIN; map = 3; }
;     else if ((r -= TR_IN) < TR_OUT) { W = p.in[IN_OWO]; WT = (bf16*)(p.ws + WS_WOO); K = D; N = D; map = 0; }
;     else if ((r -= TR_OUT) < TR_FI) TR_FFN_IN(3)
;     else { r -= TR_FI; TR_FFN_OUT(3) }
;     ...
;     const int nblk = N / 64, kb = r / nblk, nb = r % nblk, k0 = 64 * kb, n0 = 64 * nb;
; __device__ __forceinline__ void tail_convert(const Params& p, LAS unsigned char* lds, int slot, int units, int lane, int wave) {
;     const int G = gridDim.x, c = blockIdx.x, rem = units % G;
;     if (rem != 0 && c < rem) return;
;     const int nw = rem ? G - rem : G, j = rem ? c - rem : c;
;     tr_range(p, lds, TR_SLOT[slot] + j * 8 + wave, nw * 8, TR_SLOT[slot + 1], lane, wave);
.LBB0_1929:
	s_abs_i32 s0, s97
	s_waitcnt vmcnt(0)
	v_cvt_f32_u32_e32 v2, s0
	s_sub_i32 s1, 0, s0
	v_rcp_iflag_f32_e32 v2, v2
	s_nop 0
	v_mul_f32_e32 v2, 0x4f7ffffe, v2
	v_cvt_u32_f32_e32 v2, v2
	s_nop 0
	v_readfirstlane_b32 s2, v2
	s_mul_i32 s1, s1, s2
	s_mul_hi_u32 s1, s2, s1
	s_add_i32 s2, s2, s1
	s_mul_hi_u32 s1, s2, 0x5a0
	s_mul_i32 s1, s1, s0
	s_sub_i32 s1, 0x5a0, s1
	s_sub_i32 s2, s1, s0
	s_cmp_ge_u32 s1, s0
	s_cselect_b32 s1, s2, s1
	s_sub_i32 s2, s1, s0
	s_cmp_ge_u32 s1, s0
	s_cselect_b32 s44, s2, s1
	s_cmp_lg_u32 s44, 0
	s_cselect_b64 s[0:1], -1, 0
	s_cmp_lt_i32 s86, s44
	s_cselect_b64 s[2:3], -1, 0
	s_and_b64 s[0:1], s[0:1], s[2:3]
	s_and_b64 vcc, exec, s[0:1]
	s_cbranch_vccnz .LBB0_2078
	s_sub_i32 s0, s86, s44
	s_addk_i32 s0, 0xfe20
	s_lshl_b32 s16, s0, 3
	s_add_i32 s34, s16, s96
	s_add_i32 s33, s34, 0x9d00
	s_cmp_gt_i32 s33, 0x9fff
	s_cbranch_scc1 .LBB0_2078
	s_cmpk_gt_i32 s33, 0x15ff
	s_cbranch_scc0 .LBB0_1944
	s_cmpk_gt_u32 s33, 0x20ff
	s_cbranch_scc0 .LBB0_1945
	s_cmpk_gt_u32 s33, 0x2aff
	s_cbranch_scc0 .LBB0_1946
	s_cmpk_gt_u32 s33, 0x2eff
	s_cbranch_scc0 .LBB0_1947
	s_cmpk_gt_u32 s33, 0x44ff
	s_cbranch_scc0 .LBB0_1948
	s_cmpk_gt_u32 s33, 0x4fff
	s_cbranch_scc0 .LBB0_1949
	s_cmpk_gt_u32 s33, 0x65ff
	s_cbranch_scc0 .LBB0_1950
	s_cmpk_gt_u32 s33, 0x70ff
	s_cbranch_scc0 .LBB0_1951
	s_cmpk_gt_u32 s33, 0x7aff
	s_cbranch_scc0 .LBB0_1952
	s_cmpk_gt_u32 s33, 0x7eff
	s_cbranch_scc0 .LBB0_1953
	s_mov_b32 s12, s76
	s_cmpk_gt_u32 s33, 0x94ff
	s_mov_b64 s[8:9], -1
	s_cbranch_scc0 .LBB0_1954
	v_readlane_b32 s68, v253, 32
	v_readlane_b32 s69, v253, 33
	v_readlane_b32 s70, v253, 34
	v_readlane_b32 s71, v253, 35
	s_mov_b64 s[0:1], s[68:69]
	s_add_i32 s17, s34, 0x800
	s_mov_b64 s[2:3], s[70:71]
	s_add_u32 s2, s0, 0x8400000
	s_addc_u32 s3, s1, 0
	s_add_u32 s4, s88, 0xf600000
	v_readlane_b32 s72, v253, 36
	v_readlane_b32 s73, v253, 37
	v_readlane_b32 s74, v253, 38
	v_readlane_b32 s75, v253, 39
	v_readlane_b32 s76, v253, 40
	v_readlane_b32 s77, v253, 41
	v_readlane_b32 s78, v253, 42
	v_readlane_b32 s79, v253, 43
	v_readlane_b32 s80, v253, 44
	v_readlane_b32 s81, v253, 45
	v_readlane_b32 s82, v253, 46
	v_readlane_b32 s83, v253, 47
	s_addc_u32 s5, s89, 0
	s_mov_b64 s[0:1], 0
	s_branch .LBB0_1955

; #define LAS __attribute__((address_space(3)))
; __device__ __forceinline__ TrItem p0_item_of(const Params& p, int it, int lane) {
;     ...
;     const int nblk = N / 64, kb = r / nblk, nb = r % nblk, k0 = 64 * kb, n0 = 64 * nb;
;     TrItem t; t.src = W + (size_t)k0 * N + srccol(map, n0 + lane); t.N = N; t.K = K; t.fp8 = f8;
;     t.dst = f8 ? (bf16*)((unsigned char*)WT + (size_t)n0 * K + k0) : WT + (size_t)n0 * K + k0; return t;
; }
; __device__ __forceinline__ void tr_range(const Params& p, LAS unsigned char* lds, int first, int stride, int end, int lane, int wave) {
;     LAS float* scr = (LAS float*)(lds + wave * (64 * 65 * 4));
;     if (first >= end) return;
;     float ra[64];
;     TrItem cur = p0_item_of(p, first, lane);
; #pragma unroll
;     for (int i = 0; i < 64; ++i) ra[i] = cur.src[(size_t)i * cur.N];
.LBB0_2008:
	s_lshl_b32 s10, s19, 6
	s_ashr_i32 s11, s10, 31
	s_mul_i32 s9, s11, s0
	s_mul_hi_u32 s16, s10, s0
	s_sub_i32 s1, s97, s44
	s_mul_i32 s8, s96, 0x4100
	s_add_i32 s17, s16, s9
	s_mul_i32 s16, s10, s0
	s_lshl_b32 s70, s1, 3
	s_add_i32 s8, s8, 0
	s_lshl_b64 s[16:17], s[16:17], 2
	s_add_u32 s2, s2, s16
	s_addc_u32 s3, s3, s17
	v_ashrrev_i32_e32 v3, 31, v2
	v_lshl_add_u64 v[2:3], v[2:3], 2, s[2:3]
	s_ashr_i32 s2, s18, 31
	s_mul_hi_u32 s3, s18, s68
	s_mul_i32 s2, s2, s68
	s_add_i32 s3, s3, s2
	s_mul_i32 s2, s18, s68
	s_lshl_b64 s[16:17], s[2:3], 1
	s_add_u32 s9, s4, s16
	s_addc_u32 s18, s5, s17
	s_lshl_b64 s[16:17], s[10:11], 1
	s_add_u32 s9, s9, s16
	s_addc_u32 s16, s18, s17
	s_add_u32 s2, s4, s2
	s_addc_u32 s3, s5, s3
	s_add_u32 s4, s2, s10
	s_addc_u32 s5, s3, s11
	s_mov_b32 s1, 0
	s_and_b64 s[2:3], s[6:7], exec
	s_cselect_b32 s3, s16, s5
	s_cselect_b32 s2, s9, s4
	s_mul_i32 s4, s0, 63
	s_mov_b32 s5, s1
	v_lshl_add_u64 v[4:5], s[4:5], 2, v[2:3]
	s_mul_i32 s4, s0, 62
	global_load_dword v86, v[4:5], off
	v_lshl_add_u64 v[4:5], s[4:5], 2, v[2:3]
	s_mul_i32 s4, s0, 61
	global_load_dword v59, v[4:5], off
	v_lshl_add_u64 v[4:5], s[4:5], 2, v[2:3]
	s_mul_i32 s4, s0, 60
	global_load_dword v60, v[4:5], off
	v_lshl_add_u64 v[4:5], s[4:5], 2, v[2:3]
	s_mul_i32 s4, s0, 59
	global_load_dword v61, v[4:5], off
	v_lshl_add_u64 v[4:5], s[4:5], 2, v[2:3]
	s_mul_i32 s4, s0, 58
	global_load_dword v62, v[4:5], off
	v_lshl_add_u64 v[4:5], s[4:5], 2, v[2:3]
	s_mul_i32 s4, s0, 57
	global_load_dword v63, v[4:5], off
	v_lshl_add_u64 v[4:5], s[4:5], 2, v[2:3]
	s_mul_i32 s4, s0, 56
	global_load_dword v64, v[4:5], off
	v_lshl_add_u64 v[4:5], s[4:5], 2, v[2:3]
	s_mul_i32 s4, s0, 55
	global_load_dword v65, v[4:5], off
	v_lshl_add_u64 v[4:5], s[4:5], 2, v[2:3]
	s_mul_i32 s4, s0, 54
	global_load_dword v72, v[4:5], off
	v_lshl_add_u64 v[4:5], s[4:5], 2, v[2:3]
	s_mul_i32 s4, s0, 53
	global_load_dword v15, v[4:5], off
	v_lshl_add_u64 v[4:5], s[4:5], 2, v[2:3]
	s_mul_i32 s4, s0, 52
	global_load_dword v17, v[4:5], off
	v_lshl_add_u64 v[4:5], s[4:5], 2, v[2:3]
	s_mul_i32 s4, s0, 51
	global_load_dword v19, v[4:5], off
	v_lshl_add_u64 v[4:5], s[4:5], 2, v[2:3]
	s_mul_i32 s4, s0, 50
	global_load_dword v21, v[4:5], off
	v_lshl_add_u64 v[4:5], s[4:5], 2, v[2:3]
	s_mul_i32 s4, s0, 49
	global_load_dword v23, v[4:5], off
	v_lshl_add_u64 v[4:5], s[4:5], 2, v[2:3]
	s_mul_i32 s4, s0, 48
	global_load_dword v73, v[4:5], off
	v_lshl_add_u64 v[4:5], s[4:5], 2, v[2:3]
	s_mul_i32 s4, s0, 47
	global_load_dword v66, v[4:5], off
	v_lshl_add_u64 v[4:5], s[4:5], 2, v[2:3]
	s_mul_i32 s4, s0, 46
	global_load_dword v74, v[4:5], off
	v_lshl_add_u64 v[4:5], s[4:5], 2, v[2:3]
	s_mul_i32 s4, s0, 45
	global_load_dword v25, v[4:5], off
	v_lshl_add_u64 v[4:5], s[4:5], 2, v[2:3]
	s_mul_i32 s4, s0, 44
	global_load_dword v27, v[4:5], off
	v_lshl_add_u64 v[4:5], s[4:5], 2, v[2:3]
	s_mul_i32 s4, s0, 43
	global_load_dword v30, v[4:5], off
	v_lshl_add_u64 v[4:5], s[4:5], 2, v[2:3]
	s_mul_i32 s4, s0, 42
	global_load_dword v31, v[4:5], off
	v_lshl_add_u64 v[4:5], s[4:5], 2, v[2:3]
	s_mul_i32 s4, s0, 41
	global_load_dword v32, v[4:5], off
	v_lshl_add_u64 v[4:5], s[4:5], 2, v[2:3]
	s_mul_i32 s4, s0, 40
	global_load_dword v75, v[4:5], off
	v_lshl_add_u64 v[4:5], s[4:5], 2, v[2:3]
	s_mul_i32 s4, s0, 39
	global_load_dword v67, v[4:5], off
	v_lshl_add_u64 v[4:5], s[4:5], 2, v[2:3]
	s_mul_i32 s4, s0, 38
	global_load_dword v76, v[4:5], off
	v_lshl_add_u64 v[4:5], s[4:5], 2, v[2:3]
	s_mul_i32 s4, s0, 37
	global_load_dword v33, v[4:5], off
	v_lshl_add_u64 v[4:5], s[4:5], 2, v[2:3]
	s_mul_i32 s4, s0, 36
	global_load_dword v34, v[4:5], off
	v_lshl_add_u64 v[4:5], s[4:5], 2, v[2:3]
	s_mul_i32 s4, s0, 35
	global_load_dword v35, v[4:5], off
	v_lshl_add_u64 v[4:5], s[4:5], 2, v[2:3]
	s_mul_i32 s4, s0, 34
	global_load_dword v36, v[4:5], off
	v_lshl_add_u64 v[4:5], s[4:5], 2, v[2:3]
	s_mul_i32 s4, s0, 33
	global_load_dword v37, v[4:5], off
	v_lshl_add_u64 v[4:5], s[4:5], 2, v[2:3]
	s_lshl_b32 s4, s0, 5
	global_load_dword v77, v[4:5], off
	v_lshl_add_u64 v[4:5], s[4:5], 2, v[2:3]
	s_mul_i32 s4, s0, 31
	global_load_dword v68, v[4:5], off
	v_lshl_add_u64 v[4:5], s[4:5], 2, v[2:3]
	s_mul_i32 s4, s0, 30
	global_load_dword v78, v[4:5], off
	v_lshl_add_u64 v[4:5], s[4:5], 2, v[2:3]
	s_mul_i32 s4, s0, 29
	global_load_dword v38, v[4:5], off
	v_lshl_add_u64 v[4:5], s[4:5], 2, v[2:3]
	s_mul_i32 s4, s0, 28
	global_load_dword v39, v[4:5], off
	v_lshl_add_u64 v[4:5], s[4:5], 2, v[2:3]
	s_mul_i32 s4, s0, 27
	global_load_dword v40, v[4:5], off
	v_lshl_add_u64 v[4:5], s[4:5], 2, v[2:3]
	s_mul_i32 s4, s0, 26
	global_load_dword v41, v[4:5], off
	v_lshl_add_u64 v[4:5], s[4:5], 2, v[2:3]
	s_mul_i32 s4, s0, 25
	global_load_dword v42, v[4:5], off
	v_lshl_add_u64 v[4:5], s[4:5], 2, v[2:3]
	s_mul_i32 s4, s0, 24
	global_load_dword v79, v[4:5], off
	v_lshl_add_u64 v[4:5], s[4:5], 2, v[2:3]
	s_mul_i32 s4, s0, 23
	global_load_dword v69, v[4:5], off
	v_lshl_add_u64 v[4:5], s[4:5], 2, v[2:3]
	s_mul_i32 s4, s0, 22
	global_load_dword v80, v[4:5], off
	v_lshl_add_u64 v[4:5], s[4:5], 2, v[2:3]
	s_mul_i32 s4, s0, 21
	global_load_dword v43, v[4:5], off
	v_lshl_add_u64 v[4:5], s[4:5], 2, v[2:3]
	s_mul_i32 s4, s0, 20
	global_load_dword v44, v[4:5], off
	v_lshl_add_u64 v[4:5], s[4:5], 2, v[2:3]
	s_mul_i32 s4, s0, 19
; __device__ __forceinline__ unsigned cvt_pk_bf16(float lo, float hi) { unsigned r; asm volatile("v_cvt_pk_bf16_f32 %0, %1, %2" : "=v"(r) : "v"(lo), "v"(hi)); return r; }
; #define LAS __attribute__((address_space(3)))
; #define LDS_WAIT() asm volatile("s_waitcnt lgkmcnt(0)" ::: "memory")
; __device__ __forceinline__ void tr_range(const Params& p, LAS unsigned char* lds, int first, int stride, int end, int lane, int wave) {
;     LAS float* scr = (LAS float*)(lds + wave * (64 * 65 * 4));
;     if (first >= end) return;
;     float ra[64];
;     TrItem cur = p0_item_of(p, first, lane);
; #pragma unroll
;     for (int i = 0; i < 64; ++i) ra[i] = cur.src[(size_t)i * cur.N];
; #pragma unroll 1
;     for (int it = first; it < end; it += stride) {
; #pragma unroll
;         for (int i = 0; i < 64; ++i) scr[i * 65 + lane] = ra[i];
;         const bool more = it + stride < end;
;         TrItem nxt = cur;
;         if (more) { nxt = p0_item_of(p, it + stride, lane);
; #pragma unroll
;             for (int i = 0; i < 64; ++i) ra[i] = nxt.src[(size_t)i * nxt.N]; }
;         LDS_WAIT(); asm volatile("" ::: "memory");
;         if (cur.fp8) {
;             const int c = lane & 3;
; #pragma unroll
;             for (int j = 0; j < 4; ++j) { const int n = (lane >> 2) + 16 * j; const LAS float* s = scr + (16 * c) * 65 + n;
;                 u32x4 o;
;                 o.x = pk4_fp8(s[0 * 65] * W8_SCALE, s[1 * 65] * W8_SCALE, s[2 * 65] * W8_SCALE, s[3 * 65] * W8_SCALE);
;                 o.y = pk4_fp8(s[4 * 65] * W8_SCALE, s[5 * 65] * W8_SCALE, s[6 * 65] * W8_SCALE, s[7 * 65] * W8_SCALE);
;                 o.z = pk4_fp8(s[8 * 65] * W8_SCALE, s[9 * 65] * W8_SCALE, s[10 * 65] * W8_SCALE, s[11 * 65] * W8_SCALE);
;                 o.w = pk4_fp8(s[12 * 65] * W8_SCALE, s[13 * 65] * W8_SCALE, s[14 * 65] * W8_SCALE, s[15 * 65] * W8_SCALE);
;                 *(u32x4*)((unsigned char*)cur.dst + (size_t)n * cur.K + 16 * c) = o; }
;         } else {
;         const int c = lane & 7;
; #pragma unroll
;         for (int j = 0; j < 8; ++j) { const int n = (lane >> 3) + 8 * j; const LAS float* s = scr + (8 * c) * 65 + n;
;             u32x4 o; o.x = pg8::cvt_pk_bf16(s[0 * 65], s[1 * 65]); o.y = pg8::cvt_pk_bf16(s[2 * 65], s[3 * 65]); o.z = pg8::cvt_pk_bf16(s[4 * 65], s[5 * 65]); o.w = pg8::cvt_pk_bf16(s[6 * 65], s[7 * 65]);
	global_load_dword v45, v[4:5], off
	v_lshl_add_u64 v[4:5], s[4:5], 2, v[2:3]
	s_mul_i32 s4, s0, 18
	global_load_dword v46, v[4:5], off
	v_lshl_add_u64 v[4:5], s[4:5], 2, v[2:3]
	s_mul_i32 s4, s0, 17
	global_load_dword v47, v[4:5], off
	v_lshl_add_u64 v[4:5], s[4:5], 2, v[2:3]
	s_lshl_b32 s4, s0, 4
	global_load_dword v81, v[4:5], off
	v_lshl_add_u64 v[4:5], s[4:5], 2, v[2:3]
	s_mul_i32 s4, s0, 15
	global_load_dword v70, v[4:5], off
	v_lshl_add_u64 v[4:5], s[4:5], 2, v[2:3]
	s_mul_i32 s4, s0, 14
	global_load_dword v82, v[4:5], off
	v_lshl_add_u64 v[4:5], s[4:5], 2, v[2:3]
	s_mul_i32 s4, s0, 13
	global_load_dword v48, v[4:5], off
	v_lshl_add_u64 v[4:5], s[4:5], 2, v[2:3]
	s_mul_i32 s4, s0, 12
	global_load_dword v49, v[4:5], off
	v_lshl_add_u64 v[4:5], s[4:5], 2, v[2:3]
	s_mul_i32 s4, s0, 11
	global_load_dword v50, v[4:5], off
	v_lshl_add_u64 v[4:5], s[4:5], 2, v[2:3]
	s_mul_i32 s4, s0, 10
	global_load_dword v51, v[4:5], off
	v_lshl_add_u64 v[4:5], s[4:5], 2, v[2:3]
	s_mul_i32 s4, s0, 9
	global_load_dword v52, v[4:5], off
	v_lshl_add_u64 v[4:5], s[4:5], 2, v[2:3]
	s_lshl_b32 s4, s0, 3
	global_load_dword v83, v[4:5], off
	v_lshl_add_u64 v[4:5], s[4:5], 2, v[2:3]
	s_mul_i32 s4, s0, 7
	global_load_dword v71, v[4:5], off
	v_lshl_add_u64 v[4:5], s[4:5], 2, v[2:3]
	s_mul_i32 s4, s0, 6
	global_load_dword v84, v[4:5], off
	v_lshl_add_u64 v[4:5], s[4:5], 2, v[2:3]
	s_mul_i32 s4, s0, 5
	global_load_dword v53, v[4:5], off
	v_lshl_add_u64 v[4:5], s[4:5], 2, v[2:3]
	s_lshl_b32 s4, s0, 2
	global_load_dword v54, v[4:5], off
	v_lshl_add_u64 v[4:5], s[4:5], 2, v[2:3]
	s_mul_i32 s4, s0, 3
	global_load_dword v55, v[4:5], off
	v_lshl_add_u64 v[4:5], s[4:5], 2, v[2:3]
	s_lshl_b32 s4, s0, 1
	global_load_dword v56, v[4:5], off
	v_lshl_add_u64 v[4:5], s[4:5], 2, v[2:3]
	global_load_dword v57, v[4:5], off
	v_lshl_add_u64 v[4:5], s[0:1], 2, v[2:3]
	global_load_dword v58, v[4:5], off
	global_load_dword v85, v[2:3], off
	v_readlane_b32 s16, v253, 32
	v_readlane_b32 s18, v253, 34
	v_readlane_b32 s19, v253, 35
	v_readlane_b32 s17, v253, 33
	s_mov_b64 s[38:39], s[18:19]
	s_mov_b64 s[36:37], s[16:17]
	s_add_u32 s4, s36, 0x8400000
	s_addc_u32 s5, s37, 0
	v_writelane_b32 v252, s4, 22
	v_readlane_b32 s20, v253, 36
	v_readlane_b32 s21, v253, 37
	v_readlane_b32 s22, v253, 38
	v_readlane_b32 s23, v253, 39
	v_readlane_b32 s24, v253, 40
	v_readlane_b32 s25, v253, 41
	v_readlane_b32 s26, v253, 42
	v_readlane_b32 s27, v253, 43
	v_readlane_b32 s28, v253, 44
	v_readlane_b32 s29, v253, 45
	v_readlane_b32 s30, v253, 46
	v_readlane_b32 s31, v253, 47
	v_writelane_b32 v252, s5, 23
	s_add_u32 s4, s88, 0xf600000
	s_addc_u32 s5, s89, 0
	v_readlane_b32 s16, v253, 10
	v_writelane_b32 v252, s4, 20
	v_readlane_b32 s30, v253, 24
	v_readlane_b32 s31, v253, 25
	v_writelane_b32 v252, s5, 21
	s_add_u32 s4, s30, 0x10800000
	s_addc_u32 s5, s31, 0
	v_writelane_b32 v252, s4, 18
	s_mov_b32 s14, s76
	v_lshlrev_b32_e32 v4, 3, v0
	v_writelane_b32 v252, s5, 19
	s_add_u32 s4, s88, 0x8800000
	s_addc_u32 s5, s89, 0
	s_add_u32 s76, s88, 0x13c00000
	s_addc_u32 s77, s89, 0
	s_add_u32 s12, s36, 0x5800000
	v_writelane_b32 v252, s4, 16
	s_addc_u32 s13, s37, 0
	v_lshrrev_b32_e32 v6, 3, v1
	v_writelane_b32 v252, s5, 17
	s_add_u32 s4, s88, 0xe000000
	s_addc_u32 s5, s89, 0
	v_and_b32_e32 v4, 56, v4
	s_add_u32 s6, s30, 0xb000000
	v_mul_u32_u24_e32 v8, 0x104, v146
	v_mul_u32_u24_e32 v11, 0x104, v4
	v_and_b32_e32 v9, 60, v1
	v_lshlrev_b32_e32 v13, 2, v6
	s_addc_u32 s7, s31, 0
	v_lshl_add_u32 v3, v1, 2, s8
	v_add3_u32 v9, s8, v8, v9
	v_add3_u32 v11, s8, v11, v13
	s_add_u32 s8, s88, 0x5c00000
	s_addc_u32 s9, s89, 0
	s_add_u32 s10, s36, 0x2c00000
	s_addc_u32 s11, s37, 0
	v_readlane_b32 s17, v253, 11
	s_add_u32 s16, s88, 0xca00000
	s_addc_u32 s17, s89, 0
	v_readlane_b32 s18, v253, 12
	v_readlane_b32 s19, v253, 13
	v_readlane_b32 s20, v253, 14
	v_readlane_b32 s21, v253, 15
	v_readlane_b32 s22, v253, 16
	v_readlane_b32 s23, v253, 17
	v_readlane_b32 s24, v253, 18
	v_readlane_b32 s25, v253, 19
	v_readlane_b32 s26, v253, 20
	v_readlane_b32 s27, v253, 21
	v_readlane_b32 s28, v253, 22
	v_readlane_b32 s29, v253, 23
	v_writelane_b32 v253, s16, 56
	v_lshrrev_b32_e32 v2, 2, v1
	v_mov_b32_e32 v5, 0
	v_writelane_b32 v253, s17, 57
	s_add_u32 s16, s30, 0x5800000
	s_addc_u32 s17, s31, 0
	s_add_u32 s34, s88, 0x3000000
	s_addc_u32 s35, s89, 0
	s_add_u32 s36, s88, 0x12000000
	s_addc_u32 s37, s89, 0
	s_add_u32 s38, s88, 0x10c00000
	s_addc_u32 s39, s89, 0
	s_add_u32 s40, s88, 0xb400000
	s_addc_u32 s41, s89, 0
	s_add_u32 s42, s88, 0x400000
	s_addc_u32 s43, s89, 0
	s_lshl_b32 s0, s97, 3
	s_lshl_b32 s45, s44, 4
	s_sub_i32 s71, s0, s45
	s_lshl_b32 s0, s86, 3
	s_addk_i32 s0, 0xf100
	v_writelane_b32 v253, s16, 54
	s_add_i32 s72, s96, s0
	s_lshl_b32 s0, s44, 3
	v_and_b32_e32 v7, 31, v0
	v_mov_b32_e32 v147, v5
	v_or_b32_e32 v8, 16, v2
	v_or_b32_e32 v10, 32, v2
	v_or_b32_e32 v12, 48, v2
	v_or_b32_e32 v14, 8, v6
	v_or_b32_e32 v16, 16, v6
	v_or_b32_e32 v18, 24, v6
	v_or_b32_e32 v20, 32, v6
	v_or_b32_e32 v22, 40, v6
	v_or_b32_e32 v24, 48, v6
	v_or_b32_e32 v26, 56, v6
	v_writelane_b32 v253, s17, 55
	s_sub_i32 s73, 0x9d00, s0
	s_mov_b32 s74, 0xc3e00000
	v_lshlrev_b32_e32 v4, 1, v4
	v_mov_b32_e32 v13, 0x43e00000
	s_mov_b32 s78, s69
	s_mov_b64 s[44:45], s[2:3]
	s_mov_b32 s75, s68
	s_branch .LBB0_2011
